# P5/P6/P7 epilogue gate, T1 and residual loads and the GLA post-pass loads without the nt hint (on top of the scan/attention/P0 edits)
# speedup vs baseline: 1.0022x; 1.0022x over previous
; __device__ __forceinline__ float bf2f(short s) { return __uint_as_float(((unsigned)(unsigned short)s) << 16); }
; __device__ __forceinline__ float bf2f(u16 u) { return __uint_as_float((unsigned)u << 16); }
; __device__ __forceinline__ unsigned pk2(float lo, float hi) { f32x2_t v = {lo, hi}; bf16x2_t b = __builtin_convertvector(v, bf16x2_t); return __builtin_bit_cast(unsigned, b); }
;     __device__ __forceinline__ void operator()(const pg8::f32x4 (&acc)[2][2][4][2], const pg8::Unit& u, int wr, int wc, int fr, int fq) const {
;         const int col0 = u.pn * 256 + wc * 32 + 8 * fq;
; #pragma unroll
;         for (int ai = 0; ai < 2; ++ai) {
;             v4u gwv[4][2], twv[4][2];
; #pragma unroll
;             for (int m = 0; m < 4; ++m) { const size_t row = (size_t)u.pm * 256 + ai * 128 + wr * 64 + m * 16 + fr;
; #pragma unroll
;                 for (int bj = 0; bj < 2; ++bj) { const int col = col0 + bj * 128;
;                     gwv[m][bj] = __builtin_nontemporal_load((const v4u*)(MG + row * 2048 + MODE * 1024 + col));
;                     twv[m][bj] = (MODE == 1) ? __builtin_nontemporal_load((const v4u*)(T1 + row * 1024 + col)) : (v4u){0u, 0u, 0u, 0u}; } }
; #pragma unroll
;             for (int m = 0; m < 4; ++m) { const size_t row = (size_t)u.pm * 256 + ai * 128 + wr * 64 + m * 16 + fr;
; #pragma unroll
;                 for (int bj = 0; bj < 2; ++bj) { const int col = col0 + bj * 128;
;                     const pg8::f32x4 v0 = acc[ai][bj][m][0], v1 = acc[ai][bj][m][1];
;                     const float r[8] = {v0[0], v0[1], v0[2], v0[3], v1[0], v1[1], v1[2], v1[3]};
;                     const unsigned gws[4] = {gwv[m][bj].x, gwv[m][bj].y, gwv[m][bj].z, gwv[m][bj].w};
;                     const unsigned tws[4] = {twv[m][bj].x, twv[m][bj].y, twv[m][bj].z, twv[m][bj].w};
;                     unsigned ow[4];
; #pragma unroll
;                     for (int e = 0; e < 4; ++e) {
;                         float a0 = sigmoidf_(bf2f((u16)(gws[e] & 0xffffu))) * r[2 * e], a1 = sigmoidf_(bf2f((u16)(gws[e] >> 16))) * r[2 * e + 1];
;                         if (MODE == 1) { a0 += bf2f((u16)(tws[e] & 0xffffu)); a1 += bf2f((u16)(tws[e] >> 16)); }
;                         ow[e] = pk2(a0, a1); }
;                     v4u w = {ow[0], ow[1], ow[2], ow[3]};
;                     *(v4u*)((MODE == 0 ? T1 : MRG) + row * 1024 + col) = w; } }
.LBB0_578:
	v_lshl_or_b32 v128, s47, 8, v179
	s_ashr_i32 s47, s46, 31
	s_lshl_b64 s[48:49], s[46:47], 8
	v_lshl_add_u64 v[130:131], s[48:49], 0, v[156:157]
	v_ashrrev_i32_e32 v129, 31, v128
	v_lshlrev_b64 v[130:131], 12, v[130:131]
	v_lshl_add_u64 v[130:131], s[10:11], 0, v[130:131]
	v_lshlrev_b64 v[172:173], 1, v[128:129]
	v_lshl_add_u64 v[132:133], v[130:131], 0, v[172:173]
	global_load_dwordx4 v[184:187], v[132:133], off
	global_load_dwordx4 v[188:191], v[132:133], off offset:256
	v_or_b32_e32 v128, 0x80, v128
	v_ashrrev_i32_e32 v129, 31, v128
	v_lshlrev_b64 v[174:175], 1, v[128:129]
	v_lshl_add_u64 v[128:129], v[130:131], 0, s[14:15]
	v_lshl_add_u64 v[132:133], v[130:131], 0, s[16:17]
	v_lshl_add_u64 v[130:131], v[130:131], 0, s[18:19]
	v_lshl_add_u64 v[134:135], v[128:129], 0, v[172:173]
	v_lshl_add_u64 v[128:129], v[128:129], 0, v[174:175]
	v_lshl_add_u64 v[136:137], v[132:133], 0, v[172:173]
	v_lshl_add_u64 v[132:133], v[132:133], 0, v[174:175]
	v_lshl_add_u64 v[198:199], v[130:131], 0, v[172:173]
	v_lshl_add_u64 v[130:131], v[130:131], 0, v[174:175]
	global_load_dwordx4 v[192:195], v[134:135], off
	global_load_dwordx4 v[144:147], v[128:129], off
	global_load_dwordx4 v[140:143], v[136:137], off
	s_nop 0
	global_load_dwordx4 v[136:139], v[132:133], off
	s_nop 0
	global_load_dwordx4 v[132:135], v[198:199], off
	s_nop 0
	global_load_dwordx4 v[128:131], v[130:131], off
	s_lshl_b64 s[46:47], s[46:47], 19
	s_add_u32 s46, s64, s46
	s_addc_u32 s47, s65, s47
	v_lshl_add_u64 v[176:177], s[46:47], 0, v[158:159]
	v_lshl_add_u64 v[196:197], v[176:177], 0, v[172:173]
	s_andn2_b64 vcc, exec, s[2:3]
	s_mov_b64 s[2:3], -1
	s_waitcnt vmcnt(0)
	v_lshlrev_b32_e32 v183, 16, v184
	v_and_b32_e32 v184, 0xffff0000, v184
	v_lshlrev_b32_e32 v198, 16, v185
	v_and_b32_e32 v185, 0xffff0000, v185
	v_lshlrev_b32_e32 v199, 16, v186
	v_and_b32_e32 v186, 0xffff0000, v186
	v_lshlrev_b32_e32 v200, 16, v187
	v_and_b32_e32 v187, 0xffff0000, v187
	v_lshlrev_b32_e32 v201, 16, v188
	v_and_b32_e32 v188, 0xffff0000, v188
	v_mul_f32_e32 v183, 0xbfb8aa3b, v183
	v_mul_f32_e32 v184, 0xbfb8aa3b, v184
	v_mul_f32_e32 v198, 0xbfb8aa3b, v198
	v_mul_f32_e32 v185, 0xbfb8aa3b, v185
	v_mul_f32_e32 v199, 0xbfb8aa3b, v199
	v_mul_f32_e32 v186, 0xbfb8aa3b, v186
	v_mul_f32_e32 v200, 0xbfb8aa3b, v200
	v_mul_f32_e32 v187, 0xbfb8aa3b, v187
	v_mul_f32_e32 v188, 0xbfb8aa3b, v188
	v_exp_f32_e32 v183, v183
	v_exp_f32_e32 v184, v184
	v_exp_f32_e32 v198, v198
	v_exp_f32_e32 v185, v185
	v_exp_f32_e32 v199, v199
	v_exp_f32_e32 v186, v186
	v_exp_f32_e32 v200, v200
	v_exp_f32_e32 v187, v187
	v_exp_f32_e32 v188, v188
	v_lshlrev_b32_e32 v202, 16, v189
	v_and_b32_e32 v189, 0xffff0000, v189
	v_mul_f32_e32 v189, 0xbfb8aa3b, v189
	v_exp_f32_e32 v203, v189
	v_add_f32_e32 v183, 1.0, v183
	v_add_f32_e32 v189, 1.0, v184
	v_add_f32_e32 v198, 1.0, v198
	v_add_f32_e32 v204, 1.0, v185
	v_add_f32_e32 v199, 1.0, v199
	v_add_f32_e32 v205, 1.0, v186
	v_add_f32_e32 v200, 1.0, v200
	v_add_f32_e32 v206, 1.0, v187
	v_add_f32_e32 v207, 1.0, v188
	v_rcp_f32_e32 v184, v183
	v_rcp_f32_e32 v185, v189
	v_rcp_f32_e32 v186, v198
	v_rcp_f32_e32 v187, v204
	v_rcp_f32_e32 v188, v199
	v_rcp_f32_e32 v189, v205
	v_rcp_f32_e32 v198, v200
	v_rcp_f32_e32 v199, v206
	v_mul_f32_e32 v201, 0xbfb8aa3b, v201
	v_mul_f32_e32 v202, 0xbfb8aa3b, v202
	v_exp_f32_e32 v201, v201
	v_exp_f32_e32 v202, v202
	v_pk_mul_f32 v[124:125], v[124:125], v[184:185]
	v_pk_mul_f32 v[126:127], v[126:127], v[186:187]
	v_pk_mul_f32 v[184:185], v[120:121], v[188:189]
	v_pk_mul_f32 v[186:187], v[122:123], v[198:199]
	v_cvt_pk_bf16_f32 v120, v124, v125
	v_cvt_pk_bf16_f32 v121, v126, v127
	v_cvt_pk_bf16_f32 v122, v184, v185
	v_cvt_pk_bf16_f32 v123, v186, v187
	v_add_f32_e32 v201, 1.0, v201
	global_store_dwordx4 v[196:197], v[120:123], off
	v_rcp_f32_e32 v200, v201
	v_rcp_f32_e32 v201, v207
	v_add_f32_e32 v120, 1.0, v202
	v_add_f32_e32 v121, 1.0, v203
	v_rcp_f32_e32 v120, v120
	v_lshlrev_b32_e32 v122, 16, v190
	v_and_b32_e32 v123, 0xffff0000, v190
	v_rcp_f32_e32 v121, v121
	v_mul_f32_e32 v122, 0xbfb8aa3b, v122
	v_mul_f32_e32 v123, 0xbfb8aa3b, v123
	v_exp_f32_e32 v122, v122
	v_exp_f32_e32 v123, v123
	v_pk_mul_f32 v[116:117], v[116:117], v[200:201]
	v_pk_mul_f32 v[118:119], v[118:119], v[120:121]
	v_cvt_pk_bf16_f32 v116, v116, v117
	v_cvt_pk_bf16_f32 v117, v118, v119
	v_lshlrev_b32_e32 v118, 16, v191
	v_add_f32_e32 v122, 1.0, v122
	v_add_f32_e32 v123, 1.0, v123
	v_mul_f32_e32 v118, 0xbfb8aa3b, v118
	v_rcp_f32_e32 v122, v122
	v_rcp_f32_e32 v123, v123
	v_exp_f32_e32 v119, v118
	v_and_b32_e32 v118, 0xffff0000, v191
	v_mul_f32_e32 v118, 0xbfb8aa3b, v118
	v_exp_f32_e32 v120, v118
	v_pk_mul_f32 v[112:113], v[112:113], v[122:123]
	s_nop 0
	v_cvt_pk_bf16_f32 v118, v112, v113
	v_add_f32_e32 v112, 1.0, v119
	v_lshlrev_b32_e32 v119, 16, v192
	v_add_f32_e32 v113, 1.0, v120
	v_mul_f32_e32 v119, 0xbfb8aa3b, v119
	v_and_b32_e32 v120, 0xffff0000, v192
	v_exp_f32_e32 v119, v119
	v_mul_f32_e32 v120, 0xbfb8aa3b, v120
	v_rcp_f32_e32 v112, v112
	v_exp_f32_e32 v121, v120
	v_rcp_f32_e32 v113, v113
	v_add_f32_e32 v119, 1.0, v119
	v_rcp_f32_e32 v120, v119
	v_add_f32_e32 v119, 1.0, v121
	v_pk_mul_f32 v[112:113], v[114:115], v[112:113]
	v_rcp_f32_e32 v121, v119
	v_cvt_pk_bf16_f32 v119, v112, v113
	v_lshlrev_b32_e32 v112, 16, v193
	v_mul_f32_e32 v112, 0xbfb8aa3b, v112
	v_and_b32_e32 v113, 0xffff0000, v193
	v_exp_f32_e32 v112, v112
	v_mul_f32_e32 v113, 0xbfb8aa3b, v113
	v_exp_f32_e32 v113, v113
	v_pk_mul_f32 v[108:109], v[108:109], v[120:121]
	v_and_b32_e32 v114, 0xffff0000, v194
	v_cvt_pk_bf16_f32 v108, v108, v109
	v_add_f32_e32 v109, 1.0, v112
	v_rcp_f32_e32 v112, v109
	v_add_f32_e32 v109, 1.0, v113
; __device__ __forceinline__ float bf2f(short s) { return __uint_as_float(((unsigned)(unsigned short)s) << 16); }
; __device__ __forceinline__ float bf2f(u16 u) { return __uint_as_float((unsigned)u << 16); }
; __device__ __forceinline__ unsigned pk2(float lo, float hi) { f32x2_t v = {lo, hi}; bf16x2_t b = __builtin_convertvector(v, bf16x2_t); return __builtin_bit_cast(unsigned, b); }
; __device__ __forceinline__ float sigmoidf_(float x) { return __builtin_amdgcn_rcpf(1.f + __expf(-x)); }
;     __device__ __forceinline__ void operator()(const pg8::f32x4 (&acc)[2][2][4][2], const pg8::Unit& u, int wr, int wc, int fr, int fq) const {
;     ...
;             for (int m = 0; m < 4; ++m) { const size_t row = (size_t)u.pm * 256 + ai * 128 + wr * 64 + m * 16 + fr;
; #pragma unroll
;                 for (int bj = 0; bj < 2; ++bj) { const int col = col0 + bj * 128;
;                     const pg8::f32x4 v0 = acc[ai][bj][m][0], v1 = acc[ai][bj][m][1];
;                     const float r[8] = {v0[0], v0[1], v0[2], v0[3], v1[0], v1[1], v1[2], v1[3]};
;                     const unsigned gws[4] = {gwv[m][bj].x, gwv[m][bj].y, gwv[m][bj].z, gwv[m][bj].w};
;                     const unsigned tws[4] = {twv[m][bj].x, twv[m][bj].y, twv[m][bj].z, twv[m][bj].w};
;                     unsigned ow[4];
; #pragma unroll
;                     for (int e = 0; e < 4; ++e) {
;                         float a0 = sigmoidf_(bf2f((u16)(gws[e] & 0xffffu))) * r[2 * e], a1 = sigmoidf_(bf2f((u16)(gws[e] >> 16))) * r[2 * e + 1];
;                         if (MODE == 1) { a0 += bf2f((u16)(tws[e] & 0xffffu)); a1 += bf2f((u16)(tws[e] >> 16)); }
;                         ow[e] = pk2(a0, a1); }
;                     v4u w = {ow[0], ow[1], ow[2], ow[3]};
;                     *(v4u*)((MODE == 0 ? T1 : MRG) + row * 1024 + col) = w; } }
	v_rcp_f32_e32 v113, v109
	v_lshlrev_b32_e32 v109, 16, v194
	v_mul_f32_e32 v109, 0xbfb8aa3b, v109
	v_exp_f32_e32 v109, v109
	v_mul_f32_e32 v114, 0xbfb8aa3b, v114
	v_exp_f32_e32 v114, v114
	v_pk_mul_f32 v[110:111], v[110:111], v[112:113]
	v_lshlrev_b32_e32 v113, 16, v195
	v_add_f32_e32 v109, 1.0, v109
	v_mul_f32_e32 v113, 0xbfb8aa3b, v113
	v_rcp_f32_e32 v112, v109
	v_add_f32_e32 v109, 1.0, v114
	v_exp_f32_e32 v114, v113
	v_and_b32_e32 v113, 0xffff0000, v195
	v_mul_f32_e32 v113, 0xbfb8aa3b, v113
	v_exp_f32_e32 v115, v113
	v_rcp_f32_e32 v113, v109
	v_add_f32_e32 v109, 1.0, v114
	v_rcp_f32_e32 v114, v109
	v_add_f32_e32 v109, 1.0, v115
	v_rcp_f32_e32 v115, v109
	v_pk_mul_f32 v[104:105], v[104:105], v[112:113]
	v_lshlrev_b32_e32 v112, 16, v144
	v_and_b32_e32 v113, 0xffff0000, v144
	v_mul_f32_e32 v112, 0xbfb8aa3b, v112
	v_mul_f32_e32 v113, 0xbfb8aa3b, v113
	v_cvt_pk_bf16_f32 v109, v110, v111
	v_cvt_pk_bf16_f32 v110, v104, v105
	v_pk_mul_f32 v[104:105], v[106:107], v[114:115]
	v_exp_f32_e32 v112, v112
	v_exp_f32_e32 v113, v113
	v_cvt_pk_bf16_f32 v111, v104, v105
	v_lshl_add_u64 v[104:105], v[176:177], 0, s[20:21]
	v_lshl_add_u64 v[106:107], v[104:105], 0, v[172:173]
	global_store_dwordx4 v[106:107], v[108:111], off
	v_add_f32_e32 v106, 1.0, v112
	v_add_f32_e32 v107, 1.0, v113
	v_lshlrev_b32_e32 v108, 16, v145
	v_and_b32_e32 v109, 0xffff0000, v145
	v_mul_f32_e32 v108, 0xbfb8aa3b, v108
	v_mul_f32_e32 v109, 0xbfb8aa3b, v109
	v_rcp_f32_e32 v106, v106
	v_rcp_f32_e32 v107, v107
	v_exp_f32_e32 v108, v108
	v_exp_f32_e32 v109, v109
	global_store_dwordx4 v[196:197], v[116:119], off offset:256
	v_pk_mul_f32 v[100:101], v[100:101], v[106:107]
	v_add_f32_e32 v106, 1.0, v108
	v_add_f32_e32 v107, 1.0, v109
	v_rcp_f32_e32 v106, v106
	v_rcp_f32_e32 v107, v107
	v_lshlrev_b32_e32 v108, 16, v146
	v_and_b32_e32 v109, 0xffff0000, v146
	v_mul_f32_e32 v108, 0xbfb8aa3b, v108
	v_mul_f32_e32 v109, 0xbfb8aa3b, v109
	v_exp_f32_e32 v108, v108
	v_exp_f32_e32 v109, v109
	v_pk_mul_f32 v[102:103], v[102:103], v[106:107]
	v_cvt_pk_bf16_f32 v100, v100, v101
	v_cvt_pk_bf16_f32 v101, v102, v103
	v_lshlrev_b32_e32 v102, 16, v147
	v_mul_f32_e32 v102, 0xbfb8aa3b, v102
	v_add_f32_e32 v108, 1.0, v108
	v_add_f32_e32 v109, 1.0, v109
	v_exp_f32_e32 v103, v102
	v_and_b32_e32 v102, 0xffff0000, v147
	v_rcp_f32_e32 v108, v108
	v_rcp_f32_e32 v109, v109
	v_mul_f32_e32 v102, 0xbfb8aa3b, v102
	v_exp_f32_e32 v106, v102
	v_pk_mul_f32 v[96:97], v[96:97], v[108:109]
	s_nop 0
	v_cvt_pk_bf16_f32 v102, v96, v97
	v_add_f32_e32 v96, 1.0, v103
	v_add_f32_e32 v97, 1.0, v106
	v_lshlrev_b32_e32 v103, 16, v140
	v_rcp_f32_e32 v96, v96
	v_rcp_f32_e32 v97, v97
	v_mul_f32_e32 v103, 0xbfb8aa3b, v103
	v_and_b32_e32 v106, 0xffff0000, v140
	v_exp_f32_e32 v103, v103
	v_mul_f32_e32 v106, 0xbfb8aa3b, v106
	v_exp_f32_e32 v106, v106
	v_pk_mul_f32 v[96:97], v[98:99], v[96:97]
	v_add_f32_e32 v98, 1.0, v103
	v_cvt_pk_bf16_f32 v103, v96, v97
	v_lshl_add_u64 v[96:97], v[104:105], 0, v[174:175]
	v_add_f32_e32 v99, 1.0, v106
	global_store_dwordx4 v[96:97], v[100:103], off
	v_lshlrev_b32_e32 v96, 16, v141
	v_rcp_f32_e32 v98, v98
	v_rcp_f32_e32 v99, v99
	v_mul_f32_e32 v96, 0xbfb8aa3b, v96
	v_and_b32_e32 v97, 0xffff0000, v141
	v_exp_f32_e32 v96, v96
	v_mul_f32_e32 v97, 0xbfb8aa3b, v97
	v_exp_f32_e32 v97, v97
	v_pk_mul_f32 v[92:93], v[92:93], v[98:99]
	v_and_b32_e32 v98, 0xffff0000, v142
	v_cvt_pk_bf16_f32 v92, v92, v93
	v_add_f32_e32 v93, 1.0, v96
	v_rcp_f32_e32 v96, v93
	v_add_f32_e32 v93, 1.0, v97
	v_rcp_f32_e32 v97, v93
	v_lshlrev_b32_e32 v93, 16, v142
	v_mul_f32_e32 v93, 0xbfb8aa3b, v93
	v_exp_f32_e32 v93, v93
	v_mul_f32_e32 v98, 0xbfb8aa3b, v98
	v_exp_f32_e32 v98, v98
	v_pk_mul_f32 v[94:95], v[94:95], v[96:97]
	v_lshlrev_b32_e32 v97, 16, v143
	v_add_f32_e32 v93, 1.0, v93
	v_mul_f32_e32 v97, 0xbfb8aa3b, v97
	v_rcp_f32_e32 v96, v93
	v_add_f32_e32 v93, 1.0, v98
	v_exp_f32_e32 v98, v97
	v_and_b32_e32 v97, 0xffff0000, v143
	v_mul_f32_e32 v97, 0xbfb8aa3b, v97
	v_exp_f32_e32 v99, v97
	v_rcp_f32_e32 v97, v93
	v_add_f32_e32 v93, 1.0, v98
	v_rcp_f32_e32 v98, v93
	v_add_f32_e32 v93, 1.0, v99
	v_rcp_f32_e32 v99, v93
	v_pk_mul_f32 v[88:89], v[88:89], v[96:97]
	v_lshlrev_b32_e32 v96, 16, v136
	v_and_b32_e32 v97, 0xffff0000, v136
	v_mul_f32_e32 v96, 0xbfb8aa3b, v96
	v_mul_f32_e32 v97, 0xbfb8aa3b, v97
	v_cvt_pk_bf16_f32 v93, v94, v95
	v_cvt_pk_bf16_f32 v94, v88, v89
	v_pk_mul_f32 v[88:89], v[90:91], v[98:99]
	v_exp_f32_e32 v96, v96
	v_exp_f32_e32 v97, v97
	v_cvt_pk_bf16_f32 v95, v88, v89
	v_lshl_add_u64 v[88:89], v[176:177], 0, s[14:15]
	v_lshl_add_u64 v[90:91], v[88:89], 0, v[172:173]
	global_store_dwordx4 v[90:91], v[92:95], off
	v_add_f32_e32 v90, 1.0, v96
	v_add_f32_e32 v91, 1.0, v97
	v_lshlrev_b32_e32 v92, 16, v137
	v_and_b32_e32 v93, 0xffff0000, v137
	v_mul_f32_e32 v92, 0xbfb8aa3b, v92
	v_mul_f32_e32 v93, 0xbfb8aa3b, v93
	v_rcp_f32_e32 v90, v90
	v_rcp_f32_e32 v91, v91
	v_exp_f32_e32 v92, v92
	v_exp_f32_e32 v93, v93
	v_pk_mul_f32 v[84:85], v[84:85], v[90:91]
	v_add_f32_e32 v90, 1.0, v92
	v_add_f32_e32 v91, 1.0, v93
	v_rcp_f32_e32 v90, v90
	v_rcp_f32_e32 v91, v91
	v_lshlrev_b32_e32 v92, 16, v138
	v_and_b32_e32 v93, 0xffff0000, v138
	v_mul_f32_e32 v92, 0xbfb8aa3b, v92
	v_mul_f32_e32 v93, 0xbfb8aa3b, v93
	v_exp_f32_e32 v92, v92
	v_exp_f32_e32 v93, v93
	v_pk_mul_f32 v[86:87], v[86:87], v[90:91]
	v_cvt_pk_bf16_f32 v84, v84, v85
	v_cvt_pk_bf16_f32 v85, v86, v87
	v_lshlrev_b32_e32 v86, 16, v139
	v_mul_f32_e32 v86, 0xbfb8aa3b, v86
	v_add_f32_e32 v92, 1.0, v92
	v_add_f32_e32 v93, 1.0, v93
	v_exp_f32_e32 v87, v86
	v_and_b32_e32 v86, 0xffff0000, v139
	v_rcp_f32_e32 v92, v92
	v_rcp_f32_e32 v93, v93
	v_mul_f32_e32 v86, 0xbfb8aa3b, v86
	v_exp_f32_e32 v90, v86
; __device__ __forceinline__ float bf2f(short s) { return __uint_as_float(((unsigned)(unsigned short)s) << 16); }
; __device__ __forceinline__ float bf2f(u16 u) { return __uint_as_float((unsigned)u << 16); }
; __device__ __forceinline__ unsigned pk2(float lo, float hi) { f32x2_t v = {lo, hi}; bf16x2_t b = __builtin_convertvector(v, bf16x2_t); return __builtin_bit_cast(unsigned, b); }
;     __device__ __forceinline__ void operator()(const pg8::f32x4 (&acc)[2][2][4][2], const pg8::Unit& u, int wr, int wc, int fr, int fq) const {
;     ...
;         for (int ai = 0; ai < 2; ++ai) {
;             v4u gwv[4][2], twv[4][2];
; #pragma unroll
;             for (int m = 0; m < 4; ++m) { const size_t row = (size_t)u.pm * 256 + ai * 128 + wr * 64 + m * 16 + fr;
; #pragma unroll
;                 for (int bj = 0; bj < 2; ++bj) { const int col = col0 + bj * 128;
;                     gwv[m][bj] = __builtin_nontemporal_load((const v4u*)(MG + row * 2048 + MODE * 1024 + col));
;                     twv[m][bj] = (MODE == 1) ? __builtin_nontemporal_load((const v4u*)(T1 + row * 1024 + col)) : (v4u){0u, 0u, 0u, 0u}; } }
; #pragma unroll
;             for (int m = 0; m < 4; ++m) { const size_t row = (size_t)u.pm * 256 + ai * 128 + wr * 64 + m * 16 + fr;
; #pragma unroll
;                 for (int bj = 0; bj < 2; ++bj) { const int col = col0 + bj * 128;
;                     const pg8::f32x4 v0 = acc[ai][bj][m][0], v1 = acc[ai][bj][m][1];
;                     const float r[8] = {v0[0], v0[1], v0[2], v0[3], v1[0], v1[1], v1[2], v1[3]};
;                     const unsigned gws[4] = {gwv[m][bj].x, gwv[m][bj].y, gwv[m][bj].z, gwv[m][bj].w};
;                     const unsigned tws[4] = {twv[m][bj].x, twv[m][bj].y, twv[m][bj].z, twv[m][bj].w};
;                     unsigned ow[4];
; #pragma unroll
;                     for (int e = 0; e < 4; ++e) {
;                         float a0 = sigmoidf_(bf2f((u16)(gws[e] & 0xffffu))) * r[2 * e], a1 = sigmoidf_(bf2f((u16)(gws[e] >> 16))) * r[2 * e + 1];
;                         if (MODE == 1) { a0 += bf2f((u16)(tws[e] & 0xffffu)); a1 += bf2f((u16)(tws[e] >> 16)); }
;                         ow[e] = pk2(a0, a1); }
;                     v4u w = {ow[0], ow[1], ow[2], ow[3]};
;                     *(v4u*)((MODE == 0 ? T1 : MRG) + row * 1024 + col) = w; } }
	v_pk_mul_f32 v[80:81], v[80:81], v[92:93]
	s_nop 0
	v_cvt_pk_bf16_f32 v86, v80, v81
	v_add_f32_e32 v80, 1.0, v87
	v_add_f32_e32 v81, 1.0, v90
	v_lshlrev_b32_e32 v87, 16, v132
	v_rcp_f32_e32 v80, v80
	v_rcp_f32_e32 v81, v81
	v_mul_f32_e32 v87, 0xbfb8aa3b, v87
	v_and_b32_e32 v90, 0xffff0000, v132
	v_exp_f32_e32 v87, v87
	v_mul_f32_e32 v90, 0xbfb8aa3b, v90
	v_exp_f32_e32 v90, v90
	v_pk_mul_f32 v[80:81], v[82:83], v[80:81]
	v_add_f32_e32 v82, 1.0, v87
	v_cvt_pk_bf16_f32 v87, v80, v81
	v_lshl_add_u64 v[80:81], v[88:89], 0, v[174:175]
	v_add_f32_e32 v83, 1.0, v90
	global_store_dwordx4 v[80:81], v[84:87], off
	v_lshlrev_b32_e32 v80, 16, v133
	v_rcp_f32_e32 v82, v82
	v_rcp_f32_e32 v83, v83
	v_mul_f32_e32 v80, 0xbfb8aa3b, v80
	v_and_b32_e32 v81, 0xffff0000, v133
	v_exp_f32_e32 v80, v80
	v_mul_f32_e32 v81, 0xbfb8aa3b, v81
	v_exp_f32_e32 v81, v81
	v_pk_mul_f32 v[76:77], v[76:77], v[82:83]
	v_and_b32_e32 v82, 0xffff0000, v134
	v_cvt_pk_bf16_f32 v76, v76, v77
	v_add_f32_e32 v77, 1.0, v80
	v_rcp_f32_e32 v80, v77
	v_add_f32_e32 v77, 1.0, v81
	v_rcp_f32_e32 v81, v77
	v_lshlrev_b32_e32 v77, 16, v134
	v_mul_f32_e32 v77, 0xbfb8aa3b, v77
	v_exp_f32_e32 v77, v77
	v_mul_f32_e32 v82, 0xbfb8aa3b, v82
	v_exp_f32_e32 v82, v82
	v_pk_mul_f32 v[78:79], v[78:79], v[80:81]
	v_lshlrev_b32_e32 v81, 16, v135
	v_add_f32_e32 v77, 1.0, v77
	v_mul_f32_e32 v81, 0xbfb8aa3b, v81
	v_rcp_f32_e32 v80, v77
	v_add_f32_e32 v77, 1.0, v82
	v_exp_f32_e32 v82, v81
	v_and_b32_e32 v81, 0xffff0000, v135
	v_mul_f32_e32 v81, 0xbfb8aa3b, v81
	v_exp_f32_e32 v83, v81
	v_rcp_f32_e32 v81, v77
	v_add_f32_e32 v77, 1.0, v82
	v_rcp_f32_e32 v82, v77
	v_add_f32_e32 v77, 1.0, v83
	v_rcp_f32_e32 v83, v77
	v_pk_mul_f32 v[72:73], v[72:73], v[80:81]
	v_cvt_pk_bf16_f32 v77, v78, v79
	v_cvt_pk_bf16_f32 v78, v72, v73
	v_pk_mul_f32 v[72:73], v[74:75], v[82:83]
	v_lshlrev_b32_e32 v74, 16, v128
	v_and_b32_e32 v75, 0xffff0000, v128
	v_mul_f32_e32 v74, 0xbfb8aa3b, v74
	v_mul_f32_e32 v75, 0xbfb8aa3b, v75
	v_exp_f32_e32 v74, v74
	v_exp_f32_e32 v75, v75
	v_cvt_pk_bf16_f32 v79, v72, v73
	v_add_f32_e32 v72, 1.0, v74
	v_add_f32_e32 v73, 1.0, v75
	v_rcp_f32_e32 v72, v72
	v_rcp_f32_e32 v73, v73
	v_lshl_add_u64 v[74:75], v[176:177], 0, s[22:23]
	v_lshl_add_u64 v[80:81], v[74:75], 0, v[172:173]
	global_store_dwordx4 v[80:81], v[76:79], off
	v_pk_mul_f32 v[68:69], v[68:69], v[72:73]
	v_lshlrev_b32_e32 v72, 16, v129
	v_mul_f32_e32 v72, 0xbfb8aa3b, v72
	v_and_b32_e32 v73, 0xffff0000, v129
	v_exp_f32_e32 v72, v72
	v_mul_f32_e32 v73, 0xbfb8aa3b, v73
	v_exp_f32_e32 v73, v73
	v_cvt_pk_bf16_f32 v68, v68, v69
	v_add_f32_e32 v69, 1.0, v72
	v_rcp_f32_e32 v72, v69
	v_add_f32_e32 v69, 1.0, v73
	v_rcp_f32_e32 v73, v69
	v_lshlrev_b32_e32 v69, 16, v130
	v_mul_f32_e32 v69, 0xbfb8aa3b, v69
	v_and_b32_e32 v76, 0xffff0000, v130
	v_exp_f32_e32 v69, v69
	v_mul_f32_e32 v76, 0xbfb8aa3b, v76
	v_exp_f32_e32 v76, v76
	v_pk_mul_f32 v[70:71], v[70:71], v[72:73]
	v_lshlrev_b32_e32 v73, 16, v131
	v_add_f32_e32 v69, 1.0, v69
	v_mul_f32_e32 v73, 0xbfb8aa3b, v73
	v_rcp_f32_e32 v72, v69
	v_add_f32_e32 v69, 1.0, v76
	v_exp_f32_e32 v76, v73
	v_and_b32_e32 v73, 0xffff0000, v131
	v_mul_f32_e32 v73, 0xbfb8aa3b, v73
	v_exp_f32_e32 v77, v73
	v_rcp_f32_e32 v73, v69
	v_add_f32_e32 v69, 1.0, v76
	v_rcp_f32_e32 v76, v69
	v_add_f32_e32 v69, 1.0, v77
	v_rcp_f32_e32 v77, v69
	v_pk_mul_f32 v[64:65], v[64:65], v[72:73]
	v_cvt_pk_bf16_f32 v69, v70, v71
	v_cvt_pk_bf16_f32 v70, v64, v65
	v_pk_mul_f32 v[64:65], v[66:67], v[76:77]
	s_nop 0
	v_cvt_pk_bf16_f32 v71, v64, v65
	v_lshl_add_u64 v[64:65], v[74:75], 0, v[174:175]
	global_store_dwordx4 v[64:65], v[68:71], off
	v_lshl_add_u64 v[64:65], s[48:49], 0, v[160:161]
	v_lshlrev_b64 v[64:65], 12, v[64:65]
	v_lshl_add_u64 v[66:67], s[10:11], 0, v[64:65]
	v_lshl_add_u64 v[66:67], v[66:67], 0, v[172:173]
	global_load_dwordx4 v[84:87], v[66:67], off
	global_load_dwordx4 v[88:91], v[66:67], off offset:256
	v_or_b32_e32 v66, 0x10000, v64
	v_mov_b32_e32 v67, v65
	v_lshl_add_u64 v[66:67], s[10:11], 0, v[66:67]
	v_lshl_add_u64 v[66:67], v[66:67], 0, v[172:173]
	global_load_dwordx4 v[92:95], v[66:67], off
	global_load_dwordx4 v[80:83], v[66:67], off offset:256
	v_or_b32_e32 v66, 0x20000, v64
	v_mov_b32_e32 v67, v65
	v_lshl_add_u64 v[66:67], s[10:11], 0, v[66:67]
	v_lshl_add_u64 v[66:67], v[66:67], 0, v[172:173]
	global_load_dwordx4 v[76:79], v[66:67], off
	global_load_dwordx4 v[72:75], v[66:67], off offset:256
	v_or_b32_e32 v64, 0x30000, v64
	v_lshl_add_u64 v[64:65], s[10:11], 0, v[64:65]
	v_lshl_add_u64 v[64:65], v[64:65], 0, v[172:173]
	s_waitcnt vmcnt(5)
	v_lshlrev_b32_e32 v66, 16, v84
	v_mul_f32_e32 v66, 0xbfb8aa3b, v66
	v_and_b32_e32 v67, 0xffff0000, v84
	v_exp_f32_e32 v66, v66
	v_mul_f32_e32 v67, 0xbfb8aa3b, v67
	v_exp_f32_e32 v67, v67
	v_lshlrev_b32_e32 v84, 16, v85
	v_add_f32_e32 v66, 1.0, v66
	v_rcp_f32_e32 v96, v66
	v_add_f32_e32 v66, 1.0, v67
	v_rcp_f32_e32 v97, v66
	v_mul_f32_e32 v84, 0xbfb8aa3b, v84
	v_and_b32_e32 v85, 0xffff0000, v85
	v_exp_f32_e32 v84, v84
	v_mul_f32_e32 v85, 0xbfb8aa3b, v85
	v_exp_f32_e32 v85, v85
	v_pk_mul_f32 v[60:61], v[60:61], v[96:97]
	global_load_dwordx4 v[68:71], v[64:65], off
	s_nop 0
	global_load_dwordx4 v[64:67], v[64:65], off offset:256
	v_cvt_pk_bf16_f32 v60, v60, v61
	v_add_f32_e32 v61, 1.0, v84
	v_rcp_f32_e32 v84, v61
	v_add_f32_e32 v61, 1.0, v85
	v_rcp_f32_e32 v85, v61
	v_lshlrev_b32_e32 v61, 16, v86
	v_mul_f32_e32 v61, 0xbfb8aa3b, v61
	v_and_b32_e32 v86, 0xffff0000, v86
	v_exp_f32_e32 v61, v61
	v_mul_f32_e32 v86, 0xbfb8aa3b, v86
	v_exp_f32_e32 v86, v86
	v_pk_mul_f32 v[62:63], v[62:63], v[84:85]
	v_lshlrev_b32_e32 v85, 16, v87
	v_add_f32_e32 v61, 1.0, v61
	v_mul_f32_e32 v85, 0xbfb8aa3b, v85
	v_rcp_f32_e32 v84, v61
	v_add_f32_e32 v61, 1.0, v86
	v_exp_f32_e32 v86, v85
	v_and_b32_e32 v85, 0xffff0000, v87
	v_mul_f32_e32 v85, 0xbfb8aa3b, v85
	v_exp_f32_e32 v87, v85
	v_rcp_f32_e32 v85, v61
	v_add_f32_e32 v61, 1.0, v86
	v_rcp_f32_e32 v86, v61
	v_add_f32_e32 v61, 1.0, v87
	v_rcp_f32_e32 v87, v61
	v_pk_mul_f32 v[56:57], v[56:57], v[84:85]
	v_cvt_pk_bf16_f32 v61, v62, v63
	v_cvt_pk_bf16_f32 v62, v56, v57
	v_pk_mul_f32 v[56:57], v[58:59], v[86:87]
	s_waitcnt vmcnt(6)
; __device__ __forceinline__ float bf2f(short s) { return __uint_as_float(((unsigned)(unsigned short)s) << 16); }
; __device__ __forceinline__ float bf2f(u16 u) { return __uint_as_float((unsigned)u << 16); }
; __device__ __forceinline__ unsigned pk2(float lo, float hi) { f32x2_t v = {lo, hi}; bf16x2_t b = __builtin_convertvector(v, bf16x2_t); return __builtin_bit_cast(unsigned, b); }
; __device__ __forceinline__ float sigmoidf_(float x) { return __builtin_amdgcn_rcpf(1.f + __expf(-x)); }
;     __device__ __forceinline__ void operator()(const pg8::f32x4 (&acc)[2][2][4][2], const pg8::Unit& u, int wr, int wc, int fr, int fq) const {
;     ...
;             for (int m = 0; m < 4; ++m) { const size_t row = (size_t)u.pm * 256 + ai * 128 + wr * 64 + m * 16 + fr;
; #pragma unroll
;                 for (int bj = 0; bj < 2; ++bj) { const int col = col0 + bj * 128;
;                     const pg8::f32x4 v0 = acc[ai][bj][m][0], v1 = acc[ai][bj][m][1];
;                     const float r[8] = {v0[0], v0[1], v0[2], v0[3], v1[0], v1[1], v1[2], v1[3]};
;                     const unsigned gws[4] = {gwv[m][bj].x, gwv[m][bj].y, gwv[m][bj].z, gwv[m][bj].w};
;                     const unsigned tws[4] = {twv[m][bj].x, twv[m][bj].y, twv[m][bj].z, twv[m][bj].w};
;                     unsigned ow[4];
; #pragma unroll
;                     for (int e = 0; e < 4; ++e) {
;                         float a0 = sigmoidf_(bf2f((u16)(gws[e] & 0xffffu))) * r[2 * e], a1 = sigmoidf_(bf2f((u16)(gws[e] >> 16))) * r[2 * e + 1];
;                         if (MODE == 1) { a0 += bf2f((u16)(tws[e] & 0xffffu)); a1 += bf2f((u16)(tws[e] >> 16)); }
;                         ow[e] = pk2(a0, a1); }
;                     v4u w = {ow[0], ow[1], ow[2], ow[3]};
;                     *(v4u*)((MODE == 0 ? T1 : MRG) + row * 1024 + col) = w; } }
	v_lshlrev_b32_e32 v58, 16, v88
	v_and_b32_e32 v59, 0xffff0000, v88
	v_mul_f32_e32 v58, 0xbfb8aa3b, v58
	v_mul_f32_e32 v59, 0xbfb8aa3b, v59
	v_exp_f32_e32 v58, v58
	v_exp_f32_e32 v59, v59
	v_cvt_pk_bf16_f32 v63, v56, v57
	v_lshl_add_u64 v[56:57], s[46:47], 0, v[162:163]
	v_lshl_add_u64 v[56:57], v[56:57], 0, v[172:173]
	global_store_dwordx4 v[56:57], v[60:63], off
	v_add_f32_e32 v58, 1.0, v58
	v_add_f32_e32 v59, 1.0, v59
	v_lshlrev_b32_e32 v60, 16, v89
	v_and_b32_e32 v61, 0xffff0000, v89
	v_mul_f32_e32 v60, 0xbfb8aa3b, v60
	v_mul_f32_e32 v61, 0xbfb8aa3b, v61
	v_rcp_f32_e32 v58, v58
	v_rcp_f32_e32 v59, v59
	v_exp_f32_e32 v60, v60
	v_exp_f32_e32 v61, v61
	v_pk_mul_f32 v[52:53], v[52:53], v[58:59]
	v_add_f32_e32 v58, 1.0, v60
	v_add_f32_e32 v59, 1.0, v61
	v_rcp_f32_e32 v58, v58
	v_lshlrev_b32_e32 v60, 16, v90
	v_and_b32_e32 v61, 0xffff0000, v90
	v_rcp_f32_e32 v59, v59
	v_mul_f32_e32 v60, 0xbfb8aa3b, v60
	v_mul_f32_e32 v61, 0xbfb8aa3b, v61
	v_exp_f32_e32 v60, v60
	v_exp_f32_e32 v61, v61
	v_pk_mul_f32 v[54:55], v[54:55], v[58:59]
	v_cvt_pk_bf16_f32 v52, v52, v53
	v_cvt_pk_bf16_f32 v53, v54, v55
	v_lshlrev_b32_e32 v54, 16, v91
	v_add_f32_e32 v60, 1.0, v60
	v_add_f32_e32 v61, 1.0, v61
	v_mul_f32_e32 v54, 0xbfb8aa3b, v54
	v_rcp_f32_e32 v60, v60
	v_rcp_f32_e32 v61, v61
	v_exp_f32_e32 v55, v54
	v_and_b32_e32 v54, 0xffff0000, v91
	v_mul_f32_e32 v54, 0xbfb8aa3b, v54
	v_exp_f32_e32 v58, v54
	v_pk_mul_f32 v[48:49], v[48:49], v[60:61]
	s_nop 0
	v_cvt_pk_bf16_f32 v54, v48, v49
	v_add_f32_e32 v48, 1.0, v55
	s_waitcnt vmcnt(6)
	v_lshlrev_b32_e32 v55, 16, v92
	v_add_f32_e32 v49, 1.0, v58
	v_mul_f32_e32 v55, 0xbfb8aa3b, v55
	v_and_b32_e32 v58, 0xffff0000, v92
	v_exp_f32_e32 v55, v55
	v_mul_f32_e32 v58, 0xbfb8aa3b, v58
	v_rcp_f32_e32 v48, v48
	v_exp_f32_e32 v59, v58
	v_rcp_f32_e32 v49, v49
	v_add_f32_e32 v55, 1.0, v55
	v_rcp_f32_e32 v58, v55
	v_add_f32_e32 v55, 1.0, v59
	v_pk_mul_f32 v[48:49], v[50:51], v[48:49]
	v_rcp_f32_e32 v59, v55
	v_cvt_pk_bf16_f32 v55, v48, v49
	v_lshlrev_b32_e32 v48, 16, v93
	v_mul_f32_e32 v48, 0xbfb8aa3b, v48
	v_and_b32_e32 v49, 0xffff0000, v93
	v_exp_f32_e32 v48, v48
	v_mul_f32_e32 v49, 0xbfb8aa3b, v49
	v_exp_f32_e32 v49, v49
	v_pk_mul_f32 v[44:45], v[44:45], v[58:59]
	v_and_b32_e32 v50, 0xffff0000, v94
	v_cvt_pk_bf16_f32 v44, v44, v45
	v_add_f32_e32 v45, 1.0, v48
	v_rcp_f32_e32 v48, v45
	v_add_f32_e32 v45, 1.0, v49
	v_rcp_f32_e32 v49, v45
	v_lshlrev_b32_e32 v45, 16, v94
	v_mul_f32_e32 v45, 0xbfb8aa3b, v45
	v_exp_f32_e32 v45, v45
	v_mul_f32_e32 v50, 0xbfb8aa3b, v50
	v_exp_f32_e32 v50, v50
	v_pk_mul_f32 v[46:47], v[46:47], v[48:49]
	v_lshlrev_b32_e32 v49, 16, v95
	v_add_f32_e32 v45, 1.0, v45
	v_mul_f32_e32 v49, 0xbfb8aa3b, v49
	v_rcp_f32_e32 v48, v45
	v_add_f32_e32 v45, 1.0, v50
	v_exp_f32_e32 v50, v49
	v_and_b32_e32 v49, 0xffff0000, v95
	v_mul_f32_e32 v49, 0xbfb8aa3b, v49
	v_exp_f32_e32 v51, v49
	v_rcp_f32_e32 v49, v45
	v_add_f32_e32 v45, 1.0, v50
	v_rcp_f32_e32 v50, v45
	v_add_f32_e32 v45, 1.0, v51
	v_rcp_f32_e32 v51, v45
	v_pk_mul_f32 v[40:41], v[40:41], v[48:49]
	s_waitcnt vmcnt(5)
	v_lshlrev_b32_e32 v48, 16, v80
	v_and_b32_e32 v49, 0xffff0000, v80
	v_mul_f32_e32 v48, 0xbfb8aa3b, v48
	v_mul_f32_e32 v49, 0xbfb8aa3b, v49
	v_cvt_pk_bf16_f32 v45, v46, v47
	v_cvt_pk_bf16_f32 v46, v40, v41
	v_pk_mul_f32 v[40:41], v[42:43], v[50:51]
	v_exp_f32_e32 v48, v48
	v_exp_f32_e32 v49, v49
	v_cvt_pk_bf16_f32 v47, v40, v41
	v_lshl_add_u64 v[40:41], v[176:177], 0, s[24:25]
	v_lshl_add_u64 v[42:43], v[40:41], 0, v[172:173]
	global_store_dwordx4 v[42:43], v[44:47], off
	v_add_f32_e32 v42, 1.0, v48
	v_add_f32_e32 v43, 1.0, v49
	v_lshlrev_b32_e32 v44, 16, v81
	v_and_b32_e32 v45, 0xffff0000, v81
	v_mul_f32_e32 v44, 0xbfb8aa3b, v44
	v_mul_f32_e32 v45, 0xbfb8aa3b, v45
	v_rcp_f32_e32 v42, v42
	v_rcp_f32_e32 v43, v43
	v_exp_f32_e32 v44, v44
	v_exp_f32_e32 v45, v45
	global_store_dwordx4 v[56:57], v[52:55], off offset:256
	v_pk_mul_f32 v[36:37], v[36:37], v[42:43]
	v_add_f32_e32 v42, 1.0, v44
	v_add_f32_e32 v43, 1.0, v45
	v_rcp_f32_e32 v42, v42
	v_rcp_f32_e32 v43, v43
	v_lshlrev_b32_e32 v44, 16, v82
	v_and_b32_e32 v45, 0xffff0000, v82
	v_mul_f32_e32 v44, 0xbfb8aa3b, v44
	v_mul_f32_e32 v45, 0xbfb8aa3b, v45
	v_exp_f32_e32 v44, v44
	v_exp_f32_e32 v45, v45
	v_pk_mul_f32 v[38:39], v[38:39], v[42:43]
	v_cvt_pk_bf16_f32 v36, v36, v37
	v_cvt_pk_bf16_f32 v37, v38, v39
	v_lshlrev_b32_e32 v38, 16, v83
	v_mul_f32_e32 v38, 0xbfb8aa3b, v38
	v_add_f32_e32 v44, 1.0, v44
	v_add_f32_e32 v45, 1.0, v45
	v_exp_f32_e32 v39, v38
	v_and_b32_e32 v38, 0xffff0000, v83
	v_rcp_f32_e32 v44, v44
	v_rcp_f32_e32 v45, v45
	v_mul_f32_e32 v38, 0xbfb8aa3b, v38
	v_exp_f32_e32 v42, v38
	v_pk_mul_f32 v[32:33], v[32:33], v[44:45]
	s_nop 0
	v_cvt_pk_bf16_f32 v38, v32, v33
	v_add_f32_e32 v32, 1.0, v39
	v_add_f32_e32 v33, 1.0, v42
	s_waitcnt vmcnt(6)
	v_lshlrev_b32_e32 v39, 16, v76
	v_rcp_f32_e32 v32, v32
	v_rcp_f32_e32 v33, v33
	v_mul_f32_e32 v39, 0xbfb8aa3b, v39
	v_and_b32_e32 v42, 0xffff0000, v76
	v_exp_f32_e32 v39, v39
	v_mul_f32_e32 v42, 0xbfb8aa3b, v42
	v_exp_f32_e32 v42, v42
	v_pk_mul_f32 v[32:33], v[34:35], v[32:33]
	v_add_f32_e32 v34, 1.0, v39
	v_cvt_pk_bf16_f32 v39, v32, v33
	v_lshl_add_u64 v[32:33], v[40:41], 0, v[174:175]
	v_add_f32_e32 v35, 1.0, v42
	global_store_dwordx4 v[32:33], v[36:39], off
	v_lshlrev_b32_e32 v32, 16, v77
	v_rcp_f32_e32 v34, v34
	v_rcp_f32_e32 v35, v35
	v_mul_f32_e32 v32, 0xbfb8aa3b, v32
	v_and_b32_e32 v33, 0xffff0000, v77
	v_exp_f32_e32 v32, v32
	v_mul_f32_e32 v33, 0xbfb8aa3b, v33
	v_exp_f32_e32 v33, v33
	v_pk_mul_f32 v[28:29], v[28:29], v[34:35]
	v_and_b32_e32 v34, 0xffff0000, v78
	v_cvt_pk_bf16_f32 v28, v28, v29
	v_add_f32_e32 v29, 1.0, v32
	v_rcp_f32_e32 v32, v29
	v_add_f32_e32 v29, 1.0, v33
	v_rcp_f32_e32 v33, v29
	v_lshlrev_b32_e32 v29, 16, v78
	v_mul_f32_e32 v29, 0xbfb8aa3b, v29
	v_exp_f32_e32 v29, v29
	v_mul_f32_e32 v34, 0xbfb8aa3b, v34
	v_exp_f32_e32 v34, v34
	v_pk_mul_f32 v[30:31], v[30:31], v[32:33]
	v_lshlrev_b32_e32 v33, 16, v79
	v_add_f32_e32 v29, 1.0, v29
	v_mul_f32_e32 v33, 0xbfb8aa3b, v33
	v_rcp_f32_e32 v32, v29
	v_add_f32_e32 v29, 1.0, v34
	v_exp_f32_e32 v34, v33
	v_and_b32_e32 v33, 0xffff0000, v79
	v_mul_f32_e32 v33, 0xbfb8aa3b, v33
	v_exp_f32_e32 v35, v33
	v_rcp_f32_e32 v33, v29
	v_add_f32_e32 v29, 1.0, v34
	v_rcp_f32_e32 v34, v29
	v_add_f32_e32 v29, 1.0, v35
	v_rcp_f32_e32 v35, v29
	v_pk_mul_f32 v[24:25], v[24:25], v[32:33]
	s_waitcnt vmcnt(6)
; #define PG8_BAR __builtin_amdgcn_s_barrier()
; __device__ __forceinline__ float bf2f(short s) { return __uint_as_float(((unsigned)(unsigned short)s) << 16); }
; __device__ __forceinline__ float bf2f(u16 u) { return __uint_as_float((unsigned)u << 16); }
; template <class Epi, class Sched, bool ALIGN_EPI = false, bool SP2 = false>
; __device__ __forceinline__ void gemm_phase(PG8_LAS unsigned char* lds, const Gemm g, const Sched& S, const Epi& E, const int mk_wid) {
;     ...
;         if constexpr (ALIGN_EPI) { if (wr == 0) PG8_BAR; }
;         if constexpr (!Epi::AFTER_DRAIN) { E(acc, cur, wr, wc, fr, fq); S.done(cur); }
;         if (!has_next) break;
; #pragma unroll
;         for (int a = 0; a < 2; ++a)
; #pragma unroll
;             for (int b = 0; b < 2; ++b)
; #pragma unroll
;                 for (int m = 0; m < 4; ++m)
; #pragma unroll
;                     for (int n = 0; n < 2; ++n) acc[a][b][m][n] = (f32x4){0.f, 0.f, 0.f, 0.f};
;         cur = nxt; cA = nA; cB = nB; ++ui;
;         if constexpr (ALIGN_EPI) { if (wr == 1) PG8_BAR; }
;     __device__ __forceinline__ void operator()(const pg8::f32x4 (&acc)[2][2][4][2], const pg8::Unit& u, int wr, int wc, int fr, int fq) const {
;     ...
;             for (int m = 0; m < 4; ++m) { const size_t row = (size_t)u.pm * 256 + ai * 128 + wr * 64 + m * 16 + fr;
; #pragma unroll
;                 for (int bj = 0; bj < 2; ++bj) { const int col = col0 + bj * 128;
;                     const pg8::f32x4 v0 = acc[ai][bj][m][0], v1 = acc[ai][bj][m][1];
;                     const float r[8] = {v0[0], v0[1], v0[2], v0[3], v1[0], v1[1], v1[2], v1[3]};
;                     const unsigned gws[4] = {gwv[m][bj].x, gwv[m][bj].y, gwv[m][bj].z, gwv[m][bj].w};
;                     const unsigned tws[4] = {twv[m][bj].x, twv[m][bj].y, twv[m][bj].z, twv[m][bj].w};
;                     unsigned ow[4];
; #pragma unroll
;                     for (int e = 0; e < 4; ++e) {
;                         float a0 = sigmoidf_(bf2f((u16)(gws[e] & 0xffffu))) * r[2 * e], a1 = sigmoidf_(bf2f((u16)(gws[e] >> 16))) * r[2 * e + 1];
;                         if (MODE == 1) { a0 += bf2f((u16)(tws[e] & 0xffffu)); a1 += bf2f((u16)(tws[e] >> 16)); }
;                         ow[e] = pk2(a0, a1); }
;                     v4u w = {ow[0], ow[1], ow[2], ow[3]};
;                     *(v4u*)((MODE == 0 ? T1 : MRG) + row * 1024 + col) = w; } }
	v_lshlrev_b32_e32 v32, 16, v72
	v_and_b32_e32 v33, 0xffff0000, v72
	v_mul_f32_e32 v32, 0xbfb8aa3b, v32
	v_mul_f32_e32 v33, 0xbfb8aa3b, v33
	v_cvt_pk_bf16_f32 v29, v30, v31
	v_cvt_pk_bf16_f32 v30, v24, v25
	v_pk_mul_f32 v[24:25], v[26:27], v[34:35]
	v_exp_f32_e32 v32, v32
	v_exp_f32_e32 v33, v33
	v_cvt_pk_bf16_f32 v31, v24, v25
	v_lshl_add_u64 v[24:25], v[176:177], 0, s[26:27]
	v_lshl_add_u64 v[26:27], v[24:25], 0, v[172:173]
	global_store_dwordx4 v[26:27], v[28:31], off
	v_add_f32_e32 v26, 1.0, v32
	v_add_f32_e32 v27, 1.0, v33
	v_lshlrev_b32_e32 v28, 16, v73
	v_and_b32_e32 v29, 0xffff0000, v73
	v_mul_f32_e32 v28, 0xbfb8aa3b, v28
	v_mul_f32_e32 v29, 0xbfb8aa3b, v29
	v_rcp_f32_e32 v26, v26
	v_rcp_f32_e32 v27, v27
	v_exp_f32_e32 v28, v28
	v_exp_f32_e32 v29, v29
	v_pk_mul_f32 v[20:21], v[20:21], v[26:27]
	v_add_f32_e32 v26, 1.0, v28
	v_add_f32_e32 v27, 1.0, v29
	v_rcp_f32_e32 v26, v26
	v_rcp_f32_e32 v27, v27
	v_lshlrev_b32_e32 v28, 16, v74
	v_and_b32_e32 v29, 0xffff0000, v74
	v_mul_f32_e32 v28, 0xbfb8aa3b, v28
	v_mul_f32_e32 v29, 0xbfb8aa3b, v29
	v_exp_f32_e32 v28, v28
	v_exp_f32_e32 v29, v29
	v_pk_mul_f32 v[22:23], v[22:23], v[26:27]
	v_cvt_pk_bf16_f32 v20, v20, v21
	v_cvt_pk_bf16_f32 v21, v22, v23
	v_lshlrev_b32_e32 v22, 16, v75
	v_mul_f32_e32 v22, 0xbfb8aa3b, v22
	v_add_f32_e32 v28, 1.0, v28
	v_add_f32_e32 v29, 1.0, v29
	v_exp_f32_e32 v23, v22
	v_and_b32_e32 v22, 0xffff0000, v75
	v_rcp_f32_e32 v28, v28
	v_rcp_f32_e32 v29, v29
	v_mul_f32_e32 v22, 0xbfb8aa3b, v22
	v_exp_f32_e32 v26, v22
	v_pk_mul_f32 v[16:17], v[16:17], v[28:29]
	s_nop 0
	v_cvt_pk_bf16_f32 v22, v16, v17
	v_add_f32_e32 v16, 1.0, v23
	v_add_f32_e32 v17, 1.0, v26
	s_waitcnt vmcnt(6)
	v_lshlrev_b32_e32 v23, 16, v68
	v_rcp_f32_e32 v16, v16
	v_rcp_f32_e32 v17, v17
	v_mul_f32_e32 v23, 0xbfb8aa3b, v23
	v_and_b32_e32 v26, 0xffff0000, v68
	v_exp_f32_e32 v23, v23
	v_mul_f32_e32 v26, 0xbfb8aa3b, v26
	v_exp_f32_e32 v26, v26
	v_pk_mul_f32 v[16:17], v[18:19], v[16:17]
	v_add_f32_e32 v18, 1.0, v23
	v_cvt_pk_bf16_f32 v23, v16, v17
	v_lshl_add_u64 v[16:17], v[24:25], 0, v[174:175]
	v_add_f32_e32 v19, 1.0, v26
	global_store_dwordx4 v[16:17], v[20:23], off
	v_lshlrev_b32_e32 v16, 16, v69
	v_rcp_f32_e32 v18, v18
	v_rcp_f32_e32 v19, v19
	v_mul_f32_e32 v16, 0xbfb8aa3b, v16
	v_and_b32_e32 v17, 0xffff0000, v69
	v_exp_f32_e32 v16, v16
	v_mul_f32_e32 v17, 0xbfb8aa3b, v17
	v_exp_f32_e32 v17, v17
	v_pk_mul_f32 v[12:13], v[12:13], v[18:19]
	v_and_b32_e32 v18, 0xffff0000, v70
	v_cvt_pk_bf16_f32 v12, v12, v13
	v_add_f32_e32 v13, 1.0, v16
	v_rcp_f32_e32 v16, v13
	v_add_f32_e32 v13, 1.0, v17
	v_rcp_f32_e32 v17, v13
	v_lshlrev_b32_e32 v13, 16, v70
	v_mul_f32_e32 v13, 0xbfb8aa3b, v13
	v_exp_f32_e32 v13, v13
	v_mul_f32_e32 v18, 0xbfb8aa3b, v18
	v_exp_f32_e32 v18, v18
	v_pk_mul_f32 v[14:15], v[14:15], v[16:17]
	v_lshlrev_b32_e32 v17, 16, v71
	v_add_f32_e32 v13, 1.0, v13
	v_mul_f32_e32 v17, 0xbfb8aa3b, v17
	v_rcp_f32_e32 v16, v13
	v_add_f32_e32 v13, 1.0, v18
	v_exp_f32_e32 v18, v17
	v_and_b32_e32 v17, 0xffff0000, v71
	v_mul_f32_e32 v17, 0xbfb8aa3b, v17
	v_exp_f32_e32 v19, v17
	v_rcp_f32_e32 v17, v13
	v_add_f32_e32 v13, 1.0, v18
	v_rcp_f32_e32 v18, v13
	v_add_f32_e32 v13, 1.0, v19
	v_rcp_f32_e32 v19, v13
	v_pk_mul_f32 v[8:9], v[8:9], v[16:17]
	v_cvt_pk_bf16_f32 v13, v14, v15
	v_cvt_pk_bf16_f32 v14, v8, v9
	v_pk_mul_f32 v[8:9], v[10:11], v[18:19]
	s_waitcnt vmcnt(6)
	v_lshlrev_b32_e32 v10, 16, v64
	v_and_b32_e32 v11, 0xffff0000, v64
	v_mul_f32_e32 v10, 0xbfb8aa3b, v10
	v_mul_f32_e32 v11, 0xbfb8aa3b, v11
	v_exp_f32_e32 v10, v10
	v_exp_f32_e32 v11, v11
	v_cvt_pk_bf16_f32 v15, v8, v9
	v_add_f32_e32 v8, 1.0, v10
	v_add_f32_e32 v9, 1.0, v11
	v_rcp_f32_e32 v8, v8
	v_rcp_f32_e32 v9, v9
	v_lshl_add_u64 v[10:11], v[176:177], 0, s[28:29]
	v_lshl_add_u64 v[16:17], v[10:11], 0, v[172:173]
	global_store_dwordx4 v[16:17], v[12:15], off
	v_pk_mul_f32 v[4:5], v[4:5], v[8:9]
	v_lshlrev_b32_e32 v8, 16, v65
	v_mul_f32_e32 v8, 0xbfb8aa3b, v8
	v_and_b32_e32 v9, 0xffff0000, v65
	v_exp_f32_e32 v8, v8
	v_mul_f32_e32 v9, 0xbfb8aa3b, v9
	v_exp_f32_e32 v9, v9
	v_cvt_pk_bf16_f32 v4, v4, v5
	v_add_f32_e32 v5, 1.0, v8
	v_rcp_f32_e32 v8, v5
	v_add_f32_e32 v5, 1.0, v9
	v_rcp_f32_e32 v9, v5
	v_lshlrev_b32_e32 v5, 16, v66
	v_mul_f32_e32 v5, 0xbfb8aa3b, v5
	v_and_b32_e32 v12, 0xffff0000, v66
	v_exp_f32_e32 v5, v5
	v_mul_f32_e32 v12, 0xbfb8aa3b, v12
	v_exp_f32_e32 v12, v12
	v_pk_mul_f32 v[6:7], v[6:7], v[8:9]
	v_lshlrev_b32_e32 v9, 16, v67
	v_add_f32_e32 v5, 1.0, v5
	v_mul_f32_e32 v9, 0xbfb8aa3b, v9
	v_rcp_f32_e32 v8, v5
	v_add_f32_e32 v5, 1.0, v12
	v_exp_f32_e32 v12, v9
	v_and_b32_e32 v9, 0xffff0000, v67
	v_mul_f32_e32 v9, 0xbfb8aa3b, v9
	v_exp_f32_e32 v13, v9
	v_rcp_f32_e32 v9, v5
	v_add_f32_e32 v5, 1.0, v12
	v_rcp_f32_e32 v12, v5
	v_add_f32_e32 v5, 1.0, v13
	v_rcp_f32_e32 v13, v5
	v_pk_mul_f32 v[0:1], v[0:1], v[8:9]
	v_cvt_pk_bf16_f32 v5, v6, v7
	v_cvt_pk_bf16_f32 v6, v0, v1
	v_pk_mul_f32 v[0:1], v[2:3], v[12:13]
	s_nop 0
	v_cvt_pk_bf16_f32 v7, v0, v1
	v_lshl_add_u64 v[0:1], v[10:11], 0, v[174:175]
	global_store_dwordx4 v[0:1], v[4:7], off
	s_cbranch_vccnz .LBB0_567
	s_andn2_b64 vcc, exec, s[4:5]
	s_cbranch_vccnz .LBB0_566
	s_barrier
	s_branch .LBB0_566

; __device__ __forceinline__ float bf2f(short s) { return __uint_as_float(((unsigned)(unsigned short)s) << 16); }
; __device__ __forceinline__ float bf2f(u16 u) { return __uint_as_float((unsigned)u << 16); }
; __device__ __forceinline__ void p_glapost(const Args& a, const int mk_wid) {
;     ...
;     for (int it0 = gw * 4; it0 < MLAT * 4; it0 += NGW * 4) {
;         v2u wf[4], wb[4], wg[4]; float o_[4][4], ss[4];
; #pragma unroll
;         for (int e = 0; e < 4; ++e) { const size_t off = (size_t)(it0 + e) * 256 + 4 * lane; wf[e] = __builtin_nontemporal_load((const v2u*)(OF + off)); wb[e] = __builtin_nontemporal_load((const v2u*)(OB + off)); wg[e] = __builtin_nontemporal_load((const v2u*)(GG + off)); }
; #pragma unroll
;         for (int e = 0; e < 4; ++e) {
;             o_[e][0] = bf2f((u16)(wf[e].x & 0xffffu)) + bf2f((u16)(wb[e].x & 0xffffu)); o_[e][1] = bf2f((u16)(wf[e].x >> 16)) + bf2f((u16)(wb[e].x >> 16));
;             o_[e][2] = bf2f((u16)(wf[e].y & 0xffffu)) + bf2f((u16)(wb[e].y & 0xffffu)); o_[e][3] = bf2f((u16)(wf[e].y >> 16)) + bf2f((u16)(wb[e].y >> 16));
;             ss[e] = (o_[e][0] * o_[e][0] + o_[e][1] * o_[e][1]) + (o_[e][2] * o_[e][2] + o_[e][3] * o_[e][3]); }
; #pragma unroll
;         for (int o = 1; o < 64; o <<= 1) {
; #pragma unroll
;             for (int e = 0; e < 4; ++e) ss[e] += __shfl_xor(ss[e], o); }
.LBB0_584:
	v_add_co_u32_e32 v16, vcc, 0xe8000000, v4
	global_load_dwordx2 v[8:9], v[4:5], off offset:-1536
	global_load_dwordx2 v[10:11], v[4:5], off offset:-1024
	v_addc_co_u32_e32 v17, vcc, -1, v5, vcc
	global_load_dwordx2 v[14:15], v[4:5], off offset:-512
	global_load_dwordx2 v[12:13], v[4:5], off
	v_add_co_u32_e32 v18, vcc, 0xfbc00000, v4
	global_load_dwordx2 v[26:27], v[16:17], off offset:-1536
	global_load_dwordx2 v[28:29], v[16:17], off offset:-1024
	global_load_dwordx2 v[30:31], v[16:17], off offset:-512
	global_load_dwordx2 v[32:33], v[16:17], off
	v_addc_co_u32_e32 v19, vcc, -1, v5, vcc
	global_load_dwordx2 v[16:17], v[18:19], off offset:-1536
	global_load_dwordx2 v[34:35], v[18:19], off offset:-1024
	global_load_dwordx2 v[36:37], v[18:19], off offset:-512
	global_load_dwordx2 v[38:39], v[18:19], off
	s_add_i32 s10, s10, s12
	s_cmp_lt_i32 s10, 0x20000
	v_lshl_add_u64 v[4:5], v[4:5], 0, s[14:15]
	s_waitcnt vmcnt(0)
	v_and_b32_e32 v41, 0xffff0000, v9
	v_lshlrev_b32_e32 v40, 16, v9
	v_and_b32_e32 v9, 0xffff0000, v8
	v_lshlrev_b32_e32 v8, 16, v8
	v_and_b32_e32 v43, 0xffff0000, v11
	v_lshlrev_b32_e32 v42, 16, v11
	v_and_b32_e32 v11, 0xffff0000, v10
	v_lshlrev_b32_e32 v10, 16, v10
	v_and_b32_e32 v49, 0xffff0000, v27
	v_lshlrev_b32_e32 v48, 16, v27
	v_and_b32_e32 v27, 0xffff0000, v26
	v_lshlrev_b32_e32 v26, 16, v26
	v_and_b32_e32 v51, 0xffff0000, v29
	v_lshlrev_b32_e32 v50, 16, v29
	v_and_b32_e32 v29, 0xffff0000, v28
	v_lshlrev_b32_e32 v28, 16, v28
	v_and_b32_e32 v45, 0xffff0000, v15
	v_lshlrev_b32_e32 v44, 16, v15
	v_and_b32_e32 v15, 0xffff0000, v14
	v_lshlrev_b32_e32 v14, 16, v14
	v_and_b32_e32 v47, 0xffff0000, v13
	v_lshlrev_b32_e32 v46, 16, v13
	v_and_b32_e32 v13, 0xffff0000, v12
	v_lshlrev_b32_e32 v12, 16, v12
	v_and_b32_e32 v53, 0xffff0000, v31
	v_lshlrev_b32_e32 v52, 16, v31
	v_and_b32_e32 v31, 0xffff0000, v30
	v_lshlrev_b32_e32 v30, 16, v30
	v_and_b32_e32 v55, 0xffff0000, v33
	v_lshlrev_b32_e32 v54, 16, v33
	v_and_b32_e32 v33, 0xffff0000, v32
	v_lshlrev_b32_e32 v32, 16, v32
	v_pk_add_f32 v[40:41], v[48:49], v[40:41]
	v_pk_add_f32 v[8:9], v[26:27], v[8:9]
	v_pk_add_f32 v[26:27], v[50:51], v[42:43]
	v_pk_add_f32 v[10:11], v[28:29], v[10:11]
	v_and_b32_e32 v43, 0xffff0000, v35
	v_lshlrev_b32_e32 v42, 16, v35
	v_and_b32_e32 v29, 0xffff0000, v34
	v_lshlrev_b32_e32 v28, 16, v34
	v_pk_add_f32 v[34:35], v[52:53], v[44:45]
	v_and_b32_e32 v45, 0xffff0000, v37
	v_lshlrev_b32_e32 v44, 16, v37
	v_pk_add_f32 v[14:15], v[30:31], v[14:15]
	v_and_b32_e32 v31, 0xffff0000, v36
	v_lshlrev_b32_e32 v30, 16, v36
	v_pk_add_f32 v[36:37], v[54:55], v[46:47]
	v_pk_add_f32 v[12:13], v[32:33], v[12:13]
	v_mov_b32_e32 v50, v9
	v_mov_b32_e32 v51, v41
	v_mov_b32_e32 v54, v11
	v_mov_b32_e32 v55, v27
	v_and_b32_e32 v47, 0xffff0000, v39
	v_lshlrev_b32_e32 v46, 16, v39
	v_and_b32_e32 v33, 0xffff0000, v38
	v_lshlrev_b32_e32 v32, 16, v38
	v_mov_b32_e32 v38, v8
	v_mov_b32_e32 v39, v40
	v_mov_b32_e32 v52, v10
	v_mov_b32_e32 v53, v26
	v_mov_b32_e32 v58, v15
	v_mov_b32_e32 v59, v35
	v_mov_b32_e32 v62, v13
	v_mov_b32_e32 v63, v37
	v_pk_mul_f32 v[50:51], v[50:51], v[50:51]
	v_pk_mul_f32 v[54:55], v[54:55], v[54:55]
	v_mov_b32_e32 v56, v14
	v_mov_b32_e32 v57, v34
	v_mov_b32_e32 v60, v12
	v_mov_b32_e32 v61, v36
	v_pk_mul_f32 v[58:59], v[58:59], v[58:59]
	v_pk_mul_f32 v[62:63], v[62:63], v[62:63]
	v_pk_fma_f32 v[38:39], v[38:39], v[38:39], v[50:51]
	v_pk_fma_f32 v[50:51], v[52:53], v[52:53], v[54:55]
	v_pk_fma_f32 v[52:53], v[56:57], v[56:57], v[58:59]
	v_pk_fma_f32 v[54:55], v[60:61], v[60:61], v[62:63]
	v_mov_b32_e32 v56, v50
	v_mov_b32_e32 v57, v38
	v_mov_b32_e32 v38, v51
	v_mov_b32_e32 v50, v54
	v_mov_b32_e32 v51, v52
	v_mov_b32_e32 v52, v55
	v_pk_add_f32 v[38:39], v[56:57], v[38:39]
	v_pk_add_f32 v[50:51], v[50:51], v[52:53]
	ds_bpermute_b32 v53, v20, v39
	ds_bpermute_b32 v52, v20, v38
	ds_bpermute_b32 v55, v20, v51
	ds_bpermute_b32 v54, v20, v50
	v_and_b32_e32 v49, 0xffff0000, v17
	v_lshlrev_b32_e32 v48, 16, v17
	s_waitcnt lgkmcnt(2)
	v_pk_add_f32 v[38:39], v[38:39], v[52:53]
	ds_bpermute_b32 v53, v21, v39
	s_waitcnt lgkmcnt(1)
	v_pk_add_f32 v[50:51], v[50:51], v[54:55]
	ds_bpermute_b32 v52, v21, v38
	ds_bpermute_b32 v55, v21, v51
	ds_bpermute_b32 v54, v21, v50
	v_and_b32_e32 v17, 0xffff0000, v16
	v_lshlrev_b32_e32 v16, 16, v16
	s_waitcnt lgkmcnt(2)
	v_pk_add_f32 v[38:39], v[38:39], v[52:53]
	ds_bpermute_b32 v53, v22, v39
	s_waitcnt lgkmcnt(1)
	v_pk_add_f32 v[50:51], v[50:51], v[54:55]
	ds_bpermute_b32 v52, v22, v38
	ds_bpermute_b32 v55, v22, v51
	ds_bpermute_b32 v54, v22, v50
	v_mul_f32_e32 v64, 0xbfb8aa3b, v16
	v_mul_f32_e32 v65, 0xbfb8aa3b, v17
	s_waitcnt lgkmcnt(2)
	v_pk_add_f32 v[38:39], v[38:39], v[52:53]
	ds_bpermute_b32 v53, v23, v39
	s_waitcnt lgkmcnt(1)
	v_pk_add_f32 v[50:51], v[50:51], v[54:55]
	ds_bpermute_b32 v52, v23, v38
	ds_bpermute_b32 v55, v23, v51
	ds_bpermute_b32 v54, v23, v50
	v_mul_f32_e32 v66, 0xbfb8aa3b, v48
	v_mul_f32_e32 v67, 0xbfb8aa3b, v49
	s_waitcnt lgkmcnt(2)
	v_pk_add_f32 v[38:39], v[38:39], v[52:53]
	ds_bpermute_b32 v53, v24, v39
	s_waitcnt lgkmcnt(1)
; __device__ __forceinline__ float bf2f(short s) { return __uint_as_float(((unsigned)(unsigned short)s) << 16); }
; __device__ __forceinline__ float bf2f(u16 u) { return __uint_as_float((unsigned)u << 16); }
; __device__ __forceinline__ unsigned pk2(float lo, float hi) { f32x2_t v = {lo, hi}; bf16x2_t b = __builtin_convertvector(v, bf16x2_t); return __builtin_bit_cast(unsigned, b); }
; __device__ __forceinline__ float sigmoidf_(float x) { return __builtin_amdgcn_rcpf(1.f + __expf(-x)); }
; __device__ __forceinline__ void p_glapost(const Args& a, const int mk_wid) {
;     ...
;     for (int it0 = gw * 4; it0 < MLAT * 4; it0 += NGW * 4) {
;         v2u wf[4], wb[4], wg[4]; float o_[4][4], ss[4];
; #pragma unroll
;         for (int e = 0; e < 4; ++e) { const size_t off = (size_t)(it0 + e) * 256 + 4 * lane; wf[e] = __builtin_nontemporal_load((const v2u*)(OF + off)); wb[e] = __builtin_nontemporal_load((const v2u*)(OB + off)); wg[e] = __builtin_nontemporal_load((const v2u*)(GG + off)); }
; #pragma unroll
;         for (int e = 0; e < 4; ++e) {
;             o_[e][0] = bf2f((u16)(wf[e].x & 0xffffu)) + bf2f((u16)(wb[e].x & 0xffffu)); o_[e][1] = bf2f((u16)(wf[e].x >> 16)) + bf2f((u16)(wb[e].x >> 16));
;             o_[e][2] = bf2f((u16)(wf[e].y & 0xffffu)) + bf2f((u16)(wb[e].y & 0xffffu)); o_[e][3] = bf2f((u16)(wf[e].y >> 16)) + bf2f((u16)(wb[e].y >> 16));
;             ss[e] = (o_[e][0] * o_[e][0] + o_[e][1] * o_[e][1]) + (o_[e][2] * o_[e][2] + o_[e][3] * o_[e][3]); }
; #pragma unroll
;         for (int o = 1; o < 64; o <<= 1) {
; #pragma unroll
;             for (int e = 0; e < 4; ++e) ss[e] += __shfl_xor(ss[e], o); }
; #pragma unroll
;         for (int e = 0; e < 4; ++e) { const float rinv = rsqrtf(ss[e] * (1.f / 256.f) + EPS);
;             const float g0 = bf2f((u16)(wg[e].x & 0xffffu)), g1 = bf2f((u16)(wg[e].x >> 16)), g2 = bf2f((u16)(wg[e].y & 0xffffu)), g3 = bf2f((u16)(wg[e].y >> 16));
;             v2u o; o.x = pk2(o_[e][0] * rinv * g.x * (g0 * sigmoidf_(g0)), o_[e][1] * rinv * g.y * (g1 * sigmoidf_(g1)));
;             o.y = pk2(o_[e][2] * rinv * g.z * (g2 * sigmoidf_(g2)), o_[e][3] * rinv * g.w * (g3 * sigmoidf_(g3)));
;             *(v2u*)(GG + (size_t)(it0 + e) * 256 + 4 * lane) = o; } }
	v_pk_add_f32 v[50:51], v[50:51], v[54:55]
	ds_bpermute_b32 v52, v24, v38
	ds_bpermute_b32 v55, v24, v51
	ds_bpermute_b32 v54, v24, v50
	v_mul_f32_e32 v68, 0xbfb8aa3b, v28
	v_mul_f32_e32 v69, 0xbfb8aa3b, v29
	s_waitcnt lgkmcnt(2)
	v_pk_add_f32 v[38:39], v[38:39], v[52:53]
	ds_bpermute_b32 v53, v25, v39
	s_waitcnt lgkmcnt(1)
	v_pk_add_f32 v[50:51], v[50:51], v[54:55]
	ds_bpermute_b32 v52, v25, v38
	ds_bpermute_b32 v55, v25, v51
	ds_bpermute_b32 v54, v25, v50
	v_mul_f32_e32 v70, 0xbfb8aa3b, v42
	v_mul_f32_e32 v71, 0xbfb8aa3b, v43
	s_waitcnt lgkmcnt(2)
	v_pk_add_f32 v[38:39], v[38:39], v[52:53]
	v_mul_f32_e32 v72, 0xbfb8aa3b, v30
	s_waitcnt lgkmcnt(0)
	v_pk_add_f32 v[50:51], v[50:51], v[54:55]
	v_pk_fma_f32 v[38:39], v[38:39], s[16:17], v[6:7] op_sel_hi:[1,0,0]
	v_mul_f32_e32 v73, 0xbfb8aa3b, v31
	v_mul_f32_e32 v74, 0xbfb8aa3b, v44
	v_mul_f32_e32 v75, 0xbfb8aa3b, v45
	v_mul_f32_e32 v76, 0xbfb8aa3b, v32
	v_mul_f32_e32 v77, 0xbfb8aa3b, v33
	v_mul_f32_e32 v78, 0xbfb8aa3b, v46
	v_mul_f32_e32 v79, 0xbfb8aa3b, v47
	v_exp_f32_e32 v64, v64
	v_exp_f32_e32 v65, v65
	v_exp_f32_e32 v66, v66
	v_exp_f32_e32 v67, v67
	v_pk_fma_f32 v[50:51], v[50:51], s[16:17], v[6:7] op_sel_hi:[1,0,0]
	v_mul_f32_e32 v52, 0x4b800000, v39
	v_cmp_gt_f32_e64 s[6:7], s9, v39
	v_exp_f32_e32 v68, v68
	v_exp_f32_e32 v69, v69
	v_exp_f32_e32 v70, v70
	v_exp_f32_e32 v71, v71
	v_exp_f32_e32 v72, v72
	v_exp_f32_e32 v73, v73
	v_exp_f32_e32 v74, v74
	v_exp_f32_e32 v75, v75
	v_exp_f32_e32 v76, v76
	v_exp_f32_e32 v77, v77
	v_exp_f32_e32 v78, v78
	v_exp_f32_e32 v79, v79
	v_mul_f32_e32 v53, 0x4b800000, v38
	v_cmp_gt_f32_e32 vcc, s9, v38
	v_mul_f32_e32 v54, 0x4b800000, v51
	v_mul_f32_e32 v55, 0x4b800000, v50
	v_cmp_gt_f32_e64 s[2:3], s9, v50
	v_cmp_gt_f32_e64 s[4:5], s9, v51
	v_cndmask_b32_e64 v39, v39, v52, s[6:7]
	v_cndmask_b32_e32 v38, v38, v53, vcc
	v_cndmask_b32_e64 v51, v51, v54, s[4:5]
	v_cndmask_b32_e64 v50, v50, v55, s[2:3]
	v_rsq_f32_e32 v39, v39
	v_rsq_f32_e32 v52, v38
	v_rsq_f32_e32 v51, v51
	v_rsq_f32_e32 v53, v50
	v_add_f32_e32 v56, 1.0, v64
	v_add_f32_e32 v57, 1.0, v65
	v_add_f32_e32 v58, 1.0, v66
	v_add_f32_e32 v59, 1.0, v67
	v_add_f32_e32 v60, 1.0, v68
	v_add_f32_e32 v61, 1.0, v69
	v_add_f32_e32 v62, 1.0, v70
	v_add_f32_e32 v63, 1.0, v71
	v_add_f32_e32 v64, 1.0, v72
	v_add_f32_e32 v65, 1.0, v73
	v_add_f32_e32 v66, 1.0, v74
	v_add_f32_e32 v67, 1.0, v75
	v_add_f32_e32 v68, 1.0, v76
	v_add_f32_e32 v69, 1.0, v77
	v_add_f32_e32 v70, 1.0, v78
	v_add_f32_e32 v71, 1.0, v79
	v_rcp_f32_e32 v56, v56
	v_rcp_f32_e32 v57, v57
	v_rcp_f32_e32 v58, v58
	v_rcp_f32_e32 v59, v59
	v_rcp_f32_e32 v60, v60
	v_rcp_f32_e32 v61, v61
	v_rcp_f32_e32 v62, v62
	v_rcp_f32_e32 v63, v63
	v_rcp_f32_e32 v64, v64
	v_rcp_f32_e32 v65, v65
	v_rcp_f32_e32 v66, v66
	v_rcp_f32_e32 v67, v67
	v_rcp_f32_e32 v68, v68
	v_rcp_f32_e32 v69, v69
	v_rcp_f32_e32 v70, v70
	v_rcp_f32_e32 v71, v71
	v_mul_f32_e32 v38, 0x45800000, v39
	v_mul_f32_e32 v50, 0x45800000, v52
	v_mul_f32_e32 v54, 0x45800000, v51
	v_mul_f32_e32 v55, 0x45800000, v53
	v_cndmask_b32_e64 v38, v39, v38, s[6:7]
	v_cndmask_b32_e32 v50, v52, v50, vcc
	v_cndmask_b32_e64 v52, v51, v54, s[4:5]
	v_cndmask_b32_e64 v54, v53, v55, s[2:3]
	v_pk_mul_f32 v[8:9], v[8:9], v[38:39] op_sel_hi:[1,0]
	v_pk_mul_f32 v[38:39], v[40:41], v[38:39] op_sel_hi:[1,0]
	v_pk_mul_f32 v[16:17], v[56:57], v[16:17]
	v_pk_mul_f32 v[48:49], v[58:59], v[48:49]
	v_pk_mul_f32 v[10:11], v[10:11], v[50:51] op_sel_hi:[1,0]
	v_pk_mul_f32 v[26:27], v[26:27], v[50:51] op_sel_hi:[1,0]
	v_pk_mul_f32 v[14:15], v[14:15], v[52:53] op_sel_hi:[1,0]
	v_pk_mul_f32 v[34:35], v[34:35], v[52:53] op_sel_hi:[1,0]
	v_pk_mul_f32 v[12:13], v[12:13], v[54:55] op_sel_hi:[1,0]
	v_pk_mul_f32 v[36:37], v[36:37], v[54:55] op_sel_hi:[1,0]
	v_pk_mul_f32 v[8:9], v[0:1], v[8:9]
	v_pk_mul_f32 v[38:39], v[2:3], v[38:39]
	v_pk_mul_f32 v[28:29], v[60:61], v[28:29]
	v_pk_mul_f32 v[42:43], v[62:63], v[42:43]
	v_pk_mul_f32 v[30:31], v[64:65], v[30:31]
	v_pk_mul_f32 v[44:45], v[66:67], v[44:45]
	v_pk_mul_f32 v[32:33], v[68:69], v[32:33]
	v_pk_mul_f32 v[46:47], v[70:71], v[46:47]
	v_pk_mul_f32 v[10:11], v[0:1], v[10:11]
	v_pk_mul_f32 v[26:27], v[2:3], v[26:27]
	v_pk_mul_f32 v[14:15], v[0:1], v[14:15]
	v_pk_mul_f32 v[34:35], v[2:3], v[34:35]
	v_pk_mul_f32 v[12:13], v[0:1], v[12:13]
	v_pk_mul_f32 v[36:37], v[2:3], v[36:37]
	v_pk_mul_f32 v[8:9], v[16:17], v[8:9]
	v_pk_mul_f32 v[16:17], v[48:49], v[38:39]
	v_pk_mul_f32 v[10:11], v[28:29], v[10:11]
	v_pk_mul_f32 v[26:27], v[42:43], v[26:27]
	v_pk_mul_f32 v[14:15], v[30:31], v[14:15]
	v_pk_mul_f32 v[28:29], v[44:45], v[34:35]
	v_pk_mul_f32 v[12:13], v[32:33], v[12:13]
	v_pk_mul_f32 v[30:31], v[46:47], v[36:37]
	v_cvt_pk_bf16_f32 v8, v8, v9
	v_cvt_pk_bf16_f32 v9, v16, v17
	v_cvt_pk_bf16_f32 v10, v10, v11
	v_cvt_pk_bf16_f32 v11, v26, v27
	v_cvt_pk_bf16_f32 v14, v14, v15
	v_cvt_pk_bf16_f32 v15, v28, v29
	v_cvt_pk_bf16_f32 v12, v12, v13
	v_cvt_pk_bf16_f32 v13, v30, v31
	global_store_dwordx2 v[18:19], v[8:9], off offset:-1536
	global_store_dwordx2 v[18:19], v[10:11], off offset:-1024
	global_store_dwordx2 v[18:19], v[14:15], off offset:-512
	global_store_dwordx2 v[18:19], v[12:13], off
	s_cbranch_scc1 .LBB0_584

;     __device__ __forceinline__ void operator()(const pg8::f32x4 (&acc)[2][2][4][2], const pg8::Unit& u, int wr, int wc, int fr, int fq) const {
;         const int col0 = u.pn * 256 + wc * 32 + 8 * fq; const int b = (u.pm * 256) / T;
;         pg8::f32x4 gv[2][2];
; #pragma unroll
;         for (int bj = 0; bj < 2; ++bj)
; #pragma unroll
;             for (int n = 0; n < 2; ++n) gv[bj][n] = *(const pg8::f32x4*)(gate + (size_t)b * 6144 + col0 + bj * 128 + n * 4);
; #pragma unroll
;         for (int ai = 0; ai < 2; ++ai) {
;             pg8::f32x4 bs[4][2][2]; v4u bw[4][2];
; #pragma unroll
;             for (int m = 0; m < 4; ++m) { const size_t off = ((size_t)u.pm * 256 + ai * 128 + wr * 64 + m * 16 + fr) * DM + col0;
; #pragma unroll
;                 for (int bj = 0; bj < 2; ++bj) {
;                     if (IN_BF16) bw[m][bj] = __builtin_nontemporal_load((const v4u*)((const u16*)base + off + bj * 128));
;                     else { bs[m][bj][0] = __builtin_nontemporal_load((const pg8::f32x4*)((const float*)base + off + bj * 128)); bs[m][bj][1] = __builtin_nontemporal_load((const pg8::f32x4*)((const float*)base + off + bj * 128 + 4)); } } }
; #pragma unroll
;             for (int m = 0; m < 4; ++m) { const size_t off = ((size_t)u.pm * 256 + ai * 128 + wr * 64 + m * 16 + fr) * DM + col0;
; #pragma unroll
;                 for (int bj = 0; bj < 2; ++bj) {
;                     pg8::f32x4 b0, b1;
;                     if (IN_BF16) { const v4u w = bw[m][bj];
;                         b0 = (pg8::f32x4){bf2f((u16)(w.x & 0xffffu)), bf2f((u16)(w.x >> 16)), bf2f((u16)(w.y & 0xffffu)), bf2f((u16)(w.y >> 16))};
;                         b1 = (pg8::f32x4){bf2f((u16)(w.z & 0xffffu)), bf2f((u16)(w.z >> 16)), bf2f((u16)(w.w & 0xffffu)), bf2f((u16)(w.w >> 16))}; }
;                     else { b0 = bs[m][bj][0]; b1 = bs[m][bj][1]; }
;                     const pg8::f32x4 o0 = b0 + gv[bj][0] * acc[ai][bj][m][0], o1 = b1 + gv[bj][1] * acc[ai][bj][m][1];
;                     if (IN_BF16) { *(pg8::f32x4*)((float*)out + off + bj * 128) = o0; *(pg8::f32x4*)((float*)out + off + bj * 128 + 4) = o1; }
;                     else { v4u w; w.x = pk2(o0[0], o0[1]); w.y = pk2(o0[2], o0[3]); w.z = pk2(o1[0], o1[1]); w.w = pk2(o1[2], o1[3]); *(v4u*)((u16*)out + off + bj * 128) = w; } } }
;         }
.LBB0_723:
	v_lshl_or_b32 v162, s31, 8, v169
	s_ashr_i32 s31, s30, 31
	s_lshr_b32 s23, s31, 29
	s_add_i32 s23, s30, s23
	s_ashr_i32 s23, s23, 3
	s_mul_hi_i32 s25, s23, 0x6000
	s_mulk_i32 s23, 0x6000
	s_add_u32 s34, s56, s23
	s_addc_u32 s35, s57, s25
	s_lshl_b64 s[30:31], s[30:31], 8
	v_ashrrev_i32_e32 v163, 31, v162
	v_lshl_add_u64 v[166:167], s[30:31], 0, v[152:153]
	v_lshlrev_b64 v[128:129], 2, v[162:163]
	v_or_b32_e32 v238, 16, v166
	v_mov_b32_e32 v239, v167
	v_lshl_add_u64 v[130:131], s[34:35], 0, v[128:129]
	v_lshl_add_u64 v[164:165], s[12:13], 0, v[128:129]
	v_lshlrev_b64 v[128:129], 12, v[166:167]
	v_lshlrev_b64 v[190:191], 12, v[238:239]
	v_lshl_add_u64 v[186:187], v[164:165], 0, v[128:129]
	v_lshl_add_u64 v[202:203], v[164:165], 0, v[190:191]
	global_load_dwordx4 v[174:177], v[186:187], off
	global_load_dwordx4 v[140:143], v[130:131], off
	global_load_dwordx4 v[136:139], v[130:131], off offset:16
	global_load_dwordx4 v[178:181], v[186:187], off offset:16
	global_load_dwordx4 v[182:185], v[186:187], off offset:512
	global_load_dwordx4 v[132:135], v[130:131], off offset:512
	s_nop 0
	global_load_dwordx4 v[128:131], v[130:131], off offset:528
	s_nop 0
	global_load_dwordx4 v[186:189], v[186:187], off offset:528
	s_nop 0
	global_load_dwordx4 v[190:193], v[202:203], off
	global_load_dwordx4 v[194:197], v[202:203], off offset:16
	global_load_dwordx4 v[198:201], v[202:203], off offset:528
	s_nop 0
	global_load_dwordx4 v[202:205], v[202:203], off offset:512
	v_or_b32_e32 v240, 32, v166
	v_mov_b32_e32 v241, v167
	v_lshlrev_b64 v[206:207], 12, v[240:241]
	v_lshl_add_u64 v[218:219], v[164:165], 0, v[206:207]
	global_load_dwordx4 v[206:209], v[218:219], off
	global_load_dwordx4 v[210:213], v[218:219], off offset:16
	global_load_dwordx4 v[214:217], v[218:219], off offset:512
	s_nop 0
	global_load_dwordx4 v[218:221], v[218:219], off offset:528
	v_or_b32_e32 v242, 48, v166
	v_mov_b32_e32 v243, v167
	v_lshlrev_b64 v[222:223], 12, v[242:243]
	v_lshl_add_u64 v[234:235], v[164:165], 0, v[222:223]
	global_load_dwordx4 v[222:225], v[234:235], off
	global_load_dwordx4 v[226:229], v[234:235], off offset:16
	global_load_dwordx4 v[230:233], v[234:235], off offset:512
	s_nop 0
	global_load_dwordx4 v[234:237], v[234:235], off offset:528
	v_lshlrev_b64 v[244:245], 11, v[166:167]
	v_lshlrev_b64 v[238:239], 11, v[238:239]
	v_lshlrev_b64 v[162:163], 1, v[162:163]
	v_lshl_add_u64 v[244:245], s[6:7], 0, v[244:245]
	v_lshl_add_u64 v[238:239], s[6:7], 0, v[238:239]
	v_lshlrev_b64 v[240:241], 11, v[240:241]
	v_lshl_add_u64 v[244:245], v[244:245], 0, v[162:163]
	v_lshl_add_u64 v[238:239], v[238:239], 0, v[162:163]
	s_andn2_b64 vcc, exec, s[2:3]
	s_mov_b64 s[2:3], -1
	s_waitcnt vmcnt(0)
	v_pk_fma_f32 v[126:127], v[126:127], v[142:143], v[176:177]
	v_pk_fma_f32 v[124:125], v[124:125], v[140:141], v[174:175]
	v_pk_fma_f32 v[122:123], v[122:123], v[138:139], v[180:181]
	v_pk_fma_f32 v[120:121], v[120:121], v[136:137], v[178:179]
	v_pk_fma_f32 v[118:119], v[118:119], v[142:143], v[192:193]
	v_pk_fma_f32 v[116:117], v[116:117], v[140:141], v[190:191]
	v_pk_fma_f32 v[114:115], v[114:115], v[138:139], v[196:197]
	v_pk_fma_f32 v[112:113], v[112:113], v[136:137], v[194:195]
	v_pk_fma_f32 v[110:111], v[110:111], v[134:135], v[184:185]
	v_pk_fma_f32 v[108:109], v[108:109], v[132:133], v[182:183]
	v_pk_fma_f32 v[174:175], v[106:107], v[130:131], v[188:189]
	v_pk_fma_f32 v[176:177], v[104:105], v[128:129], v[186:187]
	v_cvt_pk_bf16_f32 v104, v124, v125
	v_cvt_pk_bf16_f32 v105, v126, v127
	v_cvt_pk_bf16_f32 v106, v120, v121
	v_cvt_pk_bf16_f32 v107, v122, v123
	v_pk_fma_f32 v[98:99], v[98:99], v[134:135], v[204:205]
	v_pk_fma_f32 v[96:97], v[96:97], v[132:133], v[202:203]
	v_pk_fma_f32 v[120:121], v[90:91], v[130:131], v[200:201]
	v_pk_fma_f32 v[122:123], v[88:89], v[128:129], v[198:199]
	v_cvt_pk_bf16_f32 v88, v116, v117
	v_cvt_pk_bf16_f32 v89, v118, v119
	v_cvt_pk_bf16_f32 v90, v112, v113
	v_cvt_pk_bf16_f32 v91, v114, v115
	v_cvt_pk_bf16_f32 v108, v108, v109
	v_cvt_pk_bf16_f32 v109, v110, v111
	v_cvt_pk_bf16_f32 v110, v176, v177
	v_cvt_pk_bf16_f32 v111, v174, v175
	v_pk_fma_f32 v[102:103], v[102:103], v[142:143], v[208:209]
	global_store_dwordx4 v[244:245], v[104:107], off
	global_store_dwordx4 v[244:245], v[108:111], off offset:256
	v_cvt_pk_bf16_f32 v96, v96, v97
	v_cvt_pk_bf16_f32 v97, v98, v99
	v_cvt_pk_bf16_f32 v98, v122, v123
	v_cvt_pk_bf16_f32 v99, v120, v121
	global_store_dwordx4 v[238:239], v[88:91], off
	global_store_dwordx4 v[238:239], v[96:99], off offset:256
	v_pk_fma_f32 v[94:95], v[94:95], v[138:139], v[212:213]
	v_pk_fma_f32 v[88:89], v[100:101], v[140:141], v[206:207]
	v_pk_fma_f32 v[90:91], v[92:93], v[136:137], v[210:211]
	v_lshl_add_u64 v[92:93], s[6:7], 0, v[240:241]
	v_cvt_pk_bf16_f32 v88, v88, v89
	v_cvt_pk_bf16_f32 v89, v102, v103
	v_cvt_pk_bf16_f32 v90, v90, v91
	v_cvt_pk_bf16_f32 v91, v94, v95
	v_lshl_add_u64 v[92:93], v[92:93], 0, v[162:163]
	global_store_dwordx4 v[92:93], v[88:91], off
	v_pk_fma_f32 v[82:83], v[82:83], v[134:135], v[216:217]
	v_pk_fma_f32 v[80:81], v[80:81], v[132:133], v[214:215]
	v_pk_fma_f32 v[88:89], v[74:75], v[130:131], v[220:221]
	v_pk_fma_f32 v[74:75], v[72:73], v[128:129], v[218:219]
	v_cvt_pk_bf16_f32 v72, v80, v81
	v_cvt_pk_bf16_f32 v73, v82, v83
	v_cvt_pk_bf16_f32 v74, v74, v75
	v_cvt_pk_bf16_f32 v75, v88, v89
	global_store_dwordx4 v[92:93], v[72:75], off offset:256
	v_lshlrev_b64 v[80:81], 11, v[242:243]
	v_pk_fma_f32 v[76:77], v[76:77], v[136:137], v[226:227]
	v_pk_fma_f32 v[74:75], v[86:87], v[142:143], v[224:225]
	v_pk_fma_f32 v[72:73], v[84:85], v[140:141], v[222:223]
	v_pk_fma_f32 v[78:79], v[78:79], v[138:139], v[228:229]
; __device__ __forceinline__ float bf2f(short s) { return __uint_as_float(((unsigned)(unsigned short)s) << 16); }
; __device__ __forceinline__ float bf2f(u16 u) { return __uint_as_float((unsigned)u << 16); }
; __device__ __forceinline__ unsigned pk2(float lo, float hi) { f32x2_t v = {lo, hi}; bf16x2_t b = __builtin_convertvector(v, bf16x2_t); return __builtin_bit_cast(unsigned, b); }
;     __device__ __forceinline__ void operator()(const pg8::f32x4 (&acc)[2][2][4][2], const pg8::Unit& u, int wr, int wc, int fr, int fq) const {
;     ...
;         for (int ai = 0; ai < 2; ++ai) {
;             pg8::f32x4 bs[4][2][2]; v4u bw[4][2];
; #pragma unroll
;             for (int m = 0; m < 4; ++m) { const size_t off = ((size_t)u.pm * 256 + ai * 128 + wr * 64 + m * 16 + fr) * DM + col0;
; #pragma unroll
;                 for (int bj = 0; bj < 2; ++bj) {
;                     if (IN_BF16) bw[m][bj] = __builtin_nontemporal_load((const v4u*)((const u16*)base + off + bj * 128));
;                     else { bs[m][bj][0] = __builtin_nontemporal_load((const pg8::f32x4*)((const float*)base + off + bj * 128)); bs[m][bj][1] = __builtin_nontemporal_load((const pg8::f32x4*)((const float*)base + off + bj * 128 + 4)); } } }
; #pragma unroll
;             for (int m = 0; m < 4; ++m) { const size_t off = ((size_t)u.pm * 256 + ai * 128 + wr * 64 + m * 16 + fr) * DM + col0;
; #pragma unroll
;                 for (int bj = 0; bj < 2; ++bj) {
;                     pg8::f32x4 b0, b1;
;                     if (IN_BF16) { const v4u w = bw[m][bj];
;                         b0 = (pg8::f32x4){bf2f((u16)(w.x & 0xffffu)), bf2f((u16)(w.x >> 16)), bf2f((u16)(w.y & 0xffffu)), bf2f((u16)(w.y >> 16))};
;                         b1 = (pg8::f32x4){bf2f((u16)(w.z & 0xffffu)), bf2f((u16)(w.z >> 16)), bf2f((u16)(w.w & 0xffffu)), bf2f((u16)(w.w >> 16))}; }
;                     else { b0 = bs[m][bj][0]; b1 = bs[m][bj][1]; }
;                     const pg8::f32x4 o0 = b0 + gv[bj][0] * acc[ai][bj][m][0], o1 = b1 + gv[bj][1] * acc[ai][bj][m][1];
;                     if (IN_BF16) { *(pg8::f32x4*)((float*)out + off + bj * 128) = o0; *(pg8::f32x4*)((float*)out + off + bj * 128 + 4) = o1; }
;                     else { v4u w; w.x = pk2(o0[0], o0[1]); w.y = pk2(o0[2], o0[3]); w.z = pk2(o1[0], o1[1]); w.w = pk2(o1[2], o1[3]); *(v4u*)((u16*)out + off + bj * 128) = w; } } }
;         }
	v_cvt_pk_bf16_f32 v72, v72, v73
	v_cvt_pk_bf16_f32 v73, v74, v75
	v_cvt_pk_bf16_f32 v74, v76, v77
	v_lshl_add_u64 v[76:77], s[6:7], 0, v[80:81]
	v_cvt_pk_bf16_f32 v75, v78, v79
	v_lshl_add_u64 v[76:77], v[76:77], 0, v[162:163]
	global_store_dwordx4 v[76:77], v[72:75], off
	v_pk_fma_f32 v[70:71], v[70:71], v[134:135], v[232:233]
	v_pk_fma_f32 v[68:69], v[68:69], v[132:133], v[230:231]
	v_pk_fma_f32 v[72:73], v[66:67], v[130:131], v[236:237]
	v_pk_fma_f32 v[66:67], v[64:65], v[128:129], v[234:235]
	v_cvt_pk_bf16_f32 v64, v68, v69
	v_cvt_pk_bf16_f32 v65, v70, v71
	v_cvt_pk_bf16_f32 v66, v66, v67
	v_cvt_pk_bf16_f32 v67, v72, v73
	v_lshl_add_u64 v[174:175], v[166:167], 0, s[10:11]
	global_store_dwordx4 v[76:77], v[64:67], off offset:256
	v_lshl_add_u64 v[176:177], v[166:167], 0, s[16:17]
	v_lshlrev_b64 v[80:81], 12, v[176:177]
	v_lshlrev_b64 v[64:65], 12, v[174:175]
	v_lshl_add_u64 v[76:77], v[164:165], 0, v[64:65]
	global_load_dwordx4 v[64:67], v[76:77], off
	global_load_dwordx4 v[68:71], v[76:77], off offset:16
	global_load_dwordx4 v[72:75], v[76:77], off offset:512
	s_nop 0
	global_load_dwordx4 v[76:79], v[76:77], off offset:528
	v_lshl_add_u64 v[92:93], v[164:165], 0, v[80:81]
	global_load_dwordx4 v[80:83], v[92:93], off
	global_load_dwordx4 v[84:87], v[92:93], off offset:16
	global_load_dwordx4 v[88:91], v[92:93], off offset:512
	s_nop 0
	global_load_dwordx4 v[92:95], v[92:93], off offset:528
	v_lshl_add_u64 v[178:179], v[166:167], 0, s[18:19]
	v_lshlrev_b64 v[96:97], 12, v[178:179]
	v_lshl_add_u64 v[108:109], v[164:165], 0, v[96:97]
	global_load_dwordx4 v[96:99], v[108:109], off
	global_load_dwordx4 v[100:103], v[108:109], off offset:16
	global_load_dwordx4 v[104:107], v[108:109], off offset:512
	s_nop 0
	global_load_dwordx4 v[108:111], v[108:109], off offset:528
	v_lshl_add_u64 v[166:167], v[166:167], 0, s[20:21]
	v_lshlrev_b64 v[112:113], 12, v[166:167]
	v_lshl_add_u64 v[124:125], v[164:165], 0, v[112:113]
	global_load_dwordx4 v[112:115], v[124:125], off
	global_load_dwordx4 v[116:119], v[124:125], off offset:16
	global_load_dwordx4 v[120:123], v[124:125], off offset:512
	s_nop 0
	global_load_dwordx4 v[124:127], v[124:125], off offset:528
	v_lshlrev_b64 v[164:165], 11, v[174:175]
	v_lshl_add_u64 v[164:165], s[6:7], 0, v[164:165]
	v_lshl_add_u64 v[164:165], v[164:165], 0, v[162:163]
	s_waitcnt vmcnt(15)
	v_pk_fma_f32 v[62:63], v[62:63], v[142:143], v[66:67]
	v_pk_fma_f32 v[60:61], v[60:61], v[140:141], v[64:65]
	s_waitcnt vmcnt(14)
	v_pk_fma_f32 v[58:59], v[58:59], v[138:139], v[70:71]
	v_pk_fma_f32 v[56:57], v[56:57], v[136:137], v[68:69]
	s_waitcnt vmcnt(13)
	v_pk_fma_f32 v[64:65], v[54:55], v[134:135], v[74:75]
	v_pk_fma_f32 v[66:67], v[52:53], v[132:133], v[72:73]
	s_waitcnt vmcnt(12)
	v_pk_fma_f32 v[68:69], v[42:43], v[130:131], v[78:79]
	v_pk_fma_f32 v[42:43], v[40:41], v[128:129], v[76:77]
	v_cvt_pk_bf16_f32 v52, v60, v61
	v_cvt_pk_bf16_f32 v53, v62, v63
	v_cvt_pk_bf16_f32 v54, v56, v57
	v_cvt_pk_bf16_f32 v55, v58, v59
	v_cvt_pk_bf16_f32 v40, v66, v67
	v_cvt_pk_bf16_f32 v41, v64, v65
	v_cvt_pk_bf16_f32 v42, v42, v43
	v_cvt_pk_bf16_f32 v43, v68, v69
	global_store_dwordx4 v[164:165], v[52:55], off
	global_store_dwordx4 v[164:165], v[40:43], off offset:256
	s_waitcnt vmcnt(12)
	v_pk_fma_f32 v[44:45], v[44:45], v[136:137], v[84:85]
	v_lshlrev_b64 v[52:53], 11, v[176:177]
	v_pk_fma_f32 v[42:43], v[50:51], v[142:143], v[82:83]
	v_pk_fma_f32 v[40:41], v[48:49], v[140:141], v[80:81]
	v_pk_fma_f32 v[46:47], v[46:47], v[138:139], v[86:87]
	v_cvt_pk_bf16_f32 v40, v40, v41
	v_cvt_pk_bf16_f32 v41, v42, v43
	v_cvt_pk_bf16_f32 v42, v44, v45
	v_lshl_add_u64 v[44:45], s[6:7], 0, v[52:53]
	v_cvt_pk_bf16_f32 v43, v46, v47
	v_lshl_add_u64 v[44:45], v[44:45], 0, v[162:163]
	global_store_dwordx4 v[44:45], v[40:43], off
	s_waitcnt vmcnt(12)
	v_pk_fma_f32 v[34:35], v[34:35], v[134:135], v[90:91]
	v_pk_fma_f32 v[32:33], v[32:33], v[132:133], v[88:89]
	s_waitcnt vmcnt(11)
	v_pk_fma_f32 v[40:41], v[26:27], v[130:131], v[94:95]
	v_pk_fma_f32 v[26:27], v[24:25], v[128:129], v[92:93]
	v_cvt_pk_bf16_f32 v24, v32, v33
	v_cvt_pk_bf16_f32 v25, v34, v35
	v_cvt_pk_bf16_f32 v26, v26, v27
	v_cvt_pk_bf16_f32 v27, v40, v41
	global_store_dwordx4 v[44:45], v[24:27], off offset:256
	v_lshlrev_b64 v[32:33], 11, v[178:179]
	s_waitcnt vmcnt(10)
	v_pk_fma_f32 v[28:29], v[28:29], v[136:137], v[100:101]
	v_pk_fma_f32 v[26:27], v[38:39], v[142:143], v[98:99]
	v_pk_fma_f32 v[24:25], v[36:37], v[140:141], v[96:97]
	v_pk_fma_f32 v[30:31], v[30:31], v[138:139], v[102:103]
	v_cvt_pk_bf16_f32 v24, v24, v25
	v_cvt_pk_bf16_f32 v25, v26, v27
	v_cvt_pk_bf16_f32 v26, v28, v29
	v_lshl_add_u64 v[28:29], s[6:7], 0, v[32:33]
	v_cvt_pk_bf16_f32 v27, v30, v31
	v_lshl_add_u64 v[28:29], v[28:29], 0, v[162:163]
	global_store_dwordx4 v[28:29], v[24:27], off
	s_waitcnt vmcnt(10)
	v_pk_fma_f32 v[18:19], v[18:19], v[134:135], v[106:107]
	v_pk_fma_f32 v[16:17], v[16:17], v[132:133], v[104:105]
	s_waitcnt vmcnt(9)
	v_pk_fma_f32 v[24:25], v[10:11], v[130:131], v[110:111]
	v_pk_fma_f32 v[10:11], v[8:9], v[128:129], v[108:109]
	v_cvt_pk_bf16_f32 v8, v16, v17
	v_cvt_pk_bf16_f32 v9, v18, v19
	v_cvt_pk_bf16_f32 v10, v10, v11
	v_cvt_pk_bf16_f32 v11, v24, v25
	global_store_dwordx4 v[28:29], v[8:11], off offset:256
	v_lshlrev_b64 v[16:17], 11, v[166:167]
	s_waitcnt vmcnt(8)
	v_pk_fma_f32 v[12:13], v[12:13], v[136:137], v[116:117]
	v_pk_fma_f32 v[10:11], v[22:23], v[142:143], v[114:115]
	v_pk_fma_f32 v[8:9], v[20:21], v[140:141], v[112:113]
	v_pk_fma_f32 v[14:15], v[14:15], v[138:139], v[118:119]
	v_cvt_pk_bf16_f32 v8, v8, v9
	v_cvt_pk_bf16_f32 v9, v10, v11
	v_cvt_pk_bf16_f32 v10, v12, v13
	v_lshl_add_u64 v[12:13], s[6:7], 0, v[16:17]
	v_cvt_pk_bf16_f32 v11, v14, v15
	v_lshl_add_u64 v[12:13], v[12:13], 0, v[162:163]
	global_store_dwordx4 v[12:13], v[8:11], off
	s_waitcnt vmcnt(8)
	v_pk_fma_f32 v[6:7], v[6:7], v[134:135], v[122:123]
	v_pk_fma_f32 v[4:5], v[4:5], v[132:133], v[120:121]
	s_waitcnt vmcnt(7)
	v_pk_fma_f32 v[8:9], v[2:3], v[130:131], v[126:127]
	v_pk_fma_f32 v[2:3], v[0:1], v[128:129], v[124:125]
	v_cvt_pk_bf16_f32 v0, v4, v5
	v_cvt_pk_bf16_f32 v1, v6, v7
	v_cvt_pk_bf16_f32 v2, v2, v3
	v_cvt_pk_bf16_f32 v3, v8, v9
	global_store_dwordx4 v[12:13], v[0:3], off offset:256
	s_cbranch_vccnz .LBB0_712
	s_andn2_b64 vcc, exec, s[4:5]
	s_cbranch_vccnz .LBB0_711
	s_barrier
	s_branch .LBB0_711
